# swiglu epilogue: hoist 8 SS loads, one wait; drop gu1 loop-top and gu2 preheader vmcnt(0)
# speedup vs baseline: 1.0066x; 1.0066x over previous
; #define PG8_STAGE(bufoff, gbase, voff) do { _Pragma("unroll") for (int _i = 0; _i < 2; ++_i) \
;         __builtin_amdgcn_global_load_lds((const unsigned*)((const char*)(gbase) + (voff)[_i]), (PG8_LAS unsigned*)(lds + (bufoff) + ldsw + _i * 8192), 16, 0, 0); } while (0)
; #define PG8_LDA(dst, b, h) do { _Pragma("unroll") for (int m = 0; m < 4; ++m) _Pragma("unroll") for (int k = 0; k < 2; ++k) dst[m][k] = *(const PG8_LAS bf16x8*)(lds + PG8_SA(b, h) + aoff + m * 2048 + k * 1024); } while (0)
; #define PG8_LDB(dst, b, h) do { _Pragma("unroll") for (int n = 0; n < 2; ++n) _Pragma("unroll") for (int k = 0; k < 2; ++k) dst[n][k] = *(const PG8_LAS bf16x8*)(lds + PG8_SB(b, h) + boff + n * 2048 + k * 1024); } while (0)
; #define PG8_MMA(ai, bj, At, Bt) do { __builtin_amdgcn_s_setprio(1); _Pragma("unroll") for (int m = 0; m < 4; ++m) _Pragma("unroll") for (int n = 0; n < 2; ++n) _Pragma("unroll") for (int k = 0; k < 2; ++k) \
;         acc[ai][bj][m][n] = __builtin_amdgcn_mfma_f32_16x16x32_bf16(Bt[n][k], At[m][k], acc[ai][bj][m][n], 0, 0, 0); __builtin_amdgcn_s_setprio(0); } while (0)
; #define PG8_WAIT_V(n) asm volatile("s_waitcnt vmcnt(" #n ")" ::: "memory")
; #define PG8_WAIT_L(n) asm volatile("s_waitcnt lgkmcnt(" #n ")" ::: "memory")
; #define PG8_BAR __builtin_amdgcn_s_barrier()
; #define PG8_SCHED __builtin_amdgcn_sched_barrier(0)
; template <class Epi, class Sched, bool ALIGN_EPI = false, bool SP2 = false>
; __device__ __forceinline__ void gemm_phase(PG8_LAS unsigned char* lds, const Gemm g, const Sched& S, const Epi& E) {
;     ...
;             PG8_LDB(B0, 0, 0); PG8_LDB(B1, 0, 1); PG8_SCHED; PG8_LDA(At, 0, 0); PG8_STAGE(PG8_SA(1, 1), a1 + hstep, voffA);
;             PG8_WAIT_V(8); PG8_WAIT_L(0); PG8_BAR; PG8_MMA(0, 0, At, B0); PG8_MMA(0, 1, At, B1); PG8_BAR; PG8_SCHED;
;             PG8_LDA(At, 0, 1); PG8_STAGE(PG8_SB(0, 0), b2, voffB); PG8_STAGE(PG8_SB(0, 1), b2 + hstep, voffB); PG8_STAGE(PG8_SA(0, 0), a2, voffA);
;             PG8_WAIT_V(8); PG8_WAIT_L(0); PG8_BAR; PG8_MMA(1, 0, At, B0); PG8_MMA(1, 1, At, B1); PG8_BAR; PG8_SCHED;
.LBB0_499:
	s_add_i32 s22, s17, 2
	s_add_u32 s28, s2, 0x80
	s_addc_u32 s30, s3, 0
	s_add_i32 s33, 0, 0x10000
	s_cmp_eq_u32 s72, s17
	s_cselect_b32 s35, s53, s30
	s_cselect_b32 s34, s52, s28
	v_add_u32_e32 v146, s33, v148
	s_cselect_b32 s31, s55, s16
	s_cselect_b32 s30, s54, s4
	s_add_i32 s17, 0, 0x14000
	ds_read_b128 v[142:145], v146
	ds_read_b128 v[154:157], v146 offset:1024
	ds_read_b128 v[158:161], v146 offset:2048
	ds_read_b128 v[162:165], v146 offset:3072
	v_add_u32_e32 v146, s17, v148
	ds_read_b128 v[166:169], v146
	ds_read_b128 v[170:173], v146 offset:1024
	ds_read_b128 v[174:177], v146 offset:2048
	ds_read_b128 v[178:181], v146 offset:3072
	v_lshl_add_u64 v[146:147], s[2:3], 0, v[138:139]
	s_add_i32 m0, s65, 0xc000
	ds_read_b128 v[182:185], v153
	ds_read_b128 v[186:189], v153 offset:1024
	ds_read_b128 v[190:193], v153 offset:2048
	ds_read_b128 v[208:211], v153 offset:3072
	ds_read_b128 v[212:215], v153 offset:4096
	ds_read_b128 v[216:219], v153 offset:5120
	ds_read_b128 v[220:223], v153 offset:6144
	ds_read_b128 v[228:231], v153 offset:7168
	global_load_lds_dwordx4 v[146:147], off
	v_lshl_add_u64 v[146:147], s[2:3], 0, v[140:141]
	s_add_i32 m0, s65, 0xe000
	s_nop 0
	global_load_lds_dwordx4 v[146:147], off
	s_waitcnt vmcnt(8)
	s_waitcnt lgkmcnt(0)
	s_barrier
	s_setprio 1
	s_waitcnt lgkmcnt(0)
	v_mfma_f32_16x16x32_bf16 v[124:127], v[142:145], v[182:185], v[124:127]
	v_mfma_f32_16x16x32_bf16 v[120:123], v[158:161], v[182:185], v[120:123]
	v_mfma_f32_16x16x32_bf16 v[112:115], v[142:145], v[190:193], v[112:115]
	v_mfma_f32_16x16x32_bf16 v[104:107], v[158:161], v[190:193], v[104:107]
	v_mfma_f32_16x16x32_bf16 v[94:97], v[142:145], v[212:215], v[94:97]
	v_mfma_f32_16x16x32_bf16 v[86:89], v[158:161], v[212:215], v[86:89]
	v_mfma_f32_16x16x32_bf16 v[78:81], v[142:145], v[220:223], v[78:81]
	v_mfma_f32_16x16x32_bf16 v[70:73], v[158:161], v[220:223], v[70:73]
	v_mfma_f32_16x16x32_bf16 v[124:127], v[154:157], v[186:189], v[124:127]
	v_mfma_f32_16x16x32_bf16 v[120:123], v[162:165], v[186:189], v[120:123]
	v_mfma_f32_16x16x32_bf16 v[112:115], v[154:157], v[208:211], v[112:115]
	v_mfma_f32_16x16x32_bf16 v[104:107], v[162:165], v[208:211], v[104:107]
	v_mfma_f32_16x16x32_bf16 v[94:97], v[154:157], v[216:219], v[94:97]
	v_mfma_f32_16x16x32_bf16 v[86:89], v[162:165], v[216:219], v[86:89]
	v_mfma_f32_16x16x32_bf16 v[78:81], v[154:157], v[228:231], v[78:81]
	v_mfma_f32_16x16x32_bf16 v[70:73], v[162:165], v[228:231], v[70:73]
	s_setprio 0
	s_setprio 1
	v_mfma_f32_16x16x32_bf16 v[128:131], v[166:169], v[182:185], v[128:131]
	v_mfma_f32_16x16x32_bf16 v[116:119], v[174:177], v[182:185], v[116:119]
	v_mfma_f32_16x16x32_bf16 v[108:111], v[166:169], v[190:193], v[108:111]
	v_mfma_f32_16x16x32_bf16 v[100:103], v[174:177], v[190:193], v[100:103]
	v_mfma_f32_16x16x32_bf16 v[90:93], v[166:169], v[212:215], v[90:93]
	v_mfma_f32_16x16x32_bf16 v[82:85], v[174:177], v[212:215], v[82:85]
	v_mfma_f32_16x16x32_bf16 v[74:77], v[166:169], v[220:223], v[74:77]
	v_mfma_f32_16x16x32_bf16 v[66:69], v[174:177], v[220:223], v[66:69]
	v_mfma_f32_16x16x32_bf16 v[128:131], v[170:173], v[186:189], v[128:131]
	v_mfma_f32_16x16x32_bf16 v[116:119], v[178:181], v[186:189], v[116:119]
	v_mfma_f32_16x16x32_bf16 v[108:111], v[170:173], v[208:211], v[108:111]
	v_mfma_f32_16x16x32_bf16 v[100:103], v[178:181], v[208:211], v[100:103]
	v_mfma_f32_16x16x32_bf16 v[90:93], v[170:173], v[216:219], v[90:93]
	v_mfma_f32_16x16x32_bf16 v[82:85], v[178:181], v[216:219], v[82:85]
	v_mfma_f32_16x16x32_bf16 v[74:77], v[170:173], v[228:231], v[74:77]
	v_mfma_f32_16x16x32_bf16 v[66:69], v[178:181], v[228:231], v[66:69]
	s_setprio 0
	s_barrier
	s_add_i32 s28, s33, s58
	v_lshl_add_u64 v[146:147], s[30:31], 0, v[98:99]
	s_mov_b32 m0, s28
	ds_read_b128 v[182:185], v153 offset:16384
	ds_read_b128 v[186:189], v153 offset:17408
	ds_read_b128 v[190:193], v153 offset:18432
	ds_read_b128 v[208:211], v153 offset:19456
	ds_read_b128 v[212:215], v153 offset:20480
	ds_read_b128 v[216:219], v153 offset:21504
	ds_read_b128 v[220:223], v153 offset:22528
	ds_read_b128 v[228:231], v153 offset:23552
	global_load_lds_dwordx4 v[146:147], off
	s_add_i32 m0, s28, 0x2000
	v_lshl_add_u64 v[224:225], s[30:31], 0, v[132:133]
	s_add_u32 s30, s30, s8
	s_addc_u32 s31, s31, s9
	s_add_i32 s17, s17, s58
	global_load_lds_dwordx4 v[224:225], off
	v_lshl_add_u64 v[232:233], s[30:31], 0, v[98:99]
	s_mov_b32 m0, s17
	v_lshl_add_u64 v[234:235], s[30:31], 0, v[132:133]
	global_load_lds_dwordx4 v[232:233], off
	s_add_i32 m0, s17, 0x2000
	v_lshl_add_u64 v[236:237], s[34:35], 0, v[136:137]
	global_load_lds_dwordx4 v[234:235], off
	s_mov_b32 m0, s65
	v_lshl_add_u64 v[238:239], s[34:35], 0, v[134:135]
	global_load_lds_dwordx4 v[236:237], off
	s_mov_b32 m0, s66
	s_nop 0
	global_load_lds_dwordx4 v[238:239], off
	s_waitcnt vmcnt(8)
	s_waitcnt lgkmcnt(0)
	s_barrier
; #define PG8_STAGE(bufoff, gbase, voff) do { _Pragma("unroll") for (int _i = 0; _i < 2; ++_i) \
;         __builtin_amdgcn_global_load_lds((const unsigned*)((const char*)(gbase) + (voff)[_i]), (PG8_LAS unsigned*)(lds + (bufoff) + ldsw + _i * 8192), 16, 0, 0); } while (0)
; #define PG8_LDA(dst, b, h) do { _Pragma("unroll") for (int m = 0; m < 4; ++m) _Pragma("unroll") for (int k = 0; k < 2; ++k) dst[m][k] = *(const PG8_LAS bf16x8*)(lds + PG8_SA(b, h) + aoff + m * 2048 + k * 1024); } while (0)
; #define PG8_LDB(dst, b, h) do { _Pragma("unroll") for (int n = 0; n < 2; ++n) _Pragma("unroll") for (int k = 0; k < 2; ++k) dst[n][k] = *(const PG8_LAS bf16x8*)(lds + PG8_SB(b, h) + boff + n * 2048 + k * 1024); } while (0)
; #define PG8_MMA(ai, bj, At, Bt) do { __builtin_amdgcn_s_setprio(1); _Pragma("unroll") for (int m = 0; m < 4; ++m) _Pragma("unroll") for (int n = 0; n < 2; ++n) _Pragma("unroll") for (int k = 0; k < 2; ++k) \
;         acc[ai][bj][m][n] = __builtin_amdgcn_mfma_f32_16x16x32_bf16(Bt[n][k], At[m][k], acc[ai][bj][m][n], 0, 0, 0); __builtin_amdgcn_s_setprio(0); } while (0)
; #define PG8_WAIT_V(n) asm volatile("s_waitcnt vmcnt(" #n ")" ::: "memory")
; #define PG8_WAIT_L(n) asm volatile("s_waitcnt lgkmcnt(" #n ")" ::: "memory")
; #define PG8_BAR __builtin_amdgcn_s_barrier()
; #define PG8_SCHED __builtin_amdgcn_sched_barrier(0)
; template <class Epi, class Sched, bool ALIGN_EPI = false, bool SP2 = false>
; __device__ __forceinline__ void gemm_phase(PG8_LAS unsigned char* lds, const Gemm g, const Sched& S, const Epi& E) {
;     ...
;             PG8_WAIT_V(8); PG8_WAIT_L(0); PG8_BAR; PG8_MMA(1, 0, At, B0); PG8_MMA(1, 1, At, B1); PG8_BAR; PG8_SCHED;
;             PG8_LDB(B0, 1, 0); PG8_LDB(B1, 1, 1); PG8_SCHED; PG8_LDA(At, 1, 0); PG8_STAGE(PG8_SA(0, 1), a2 + hstep, voffA);
;             PG8_WAIT_V(8); PG8_WAIT_L(0); PG8_BAR; PG8_MMA(0, 0, At, B0); PG8_MMA(0, 1, At, B1); PG8_BAR; PG8_SCHED;
	s_setprio 1
	s_waitcnt lgkmcnt(0)
	v_mfma_f32_16x16x32_bf16 v[62:65], v[142:145], v[182:185], v[62:65]
	v_mfma_f32_16x16x32_bf16 v[54:57], v[158:161], v[182:185], v[54:57]
	v_mfma_f32_16x16x32_bf16 v[46:49], v[142:145], v[190:193], v[46:49]
	v_mfma_f32_16x16x32_bf16 v[38:41], v[158:161], v[190:193], v[38:41]
	v_mfma_f32_16x16x32_bf16 v[30:33], v[142:145], v[212:215], v[30:33]
	v_mfma_f32_16x16x32_bf16 v[22:25], v[158:161], v[212:215], v[22:25]
	v_mfma_f32_16x16x32_bf16 v[14:17], v[142:145], v[220:223], v[14:17]
	v_mfma_f32_16x16x32_bf16 v[6:9], v[158:161], v[220:223], v[6:9]
	v_mfma_f32_16x16x32_bf16 v[62:65], v[154:157], v[186:189], v[62:65]
	v_mfma_f32_16x16x32_bf16 v[54:57], v[162:165], v[186:189], v[54:57]
	v_mfma_f32_16x16x32_bf16 v[46:49], v[154:157], v[208:211], v[46:49]
	v_mfma_f32_16x16x32_bf16 v[38:41], v[162:165], v[208:211], v[38:41]
	v_mfma_f32_16x16x32_bf16 v[30:33], v[154:157], v[216:219], v[30:33]
	v_mfma_f32_16x16x32_bf16 v[22:25], v[162:165], v[216:219], v[22:25]
	v_mfma_f32_16x16x32_bf16 v[14:17], v[154:157], v[228:231], v[14:17]
	v_mfma_f32_16x16x32_bf16 v[6:9], v[162:165], v[228:231], v[6:9]
	s_setprio 0
	s_setprio 1
	v_mfma_f32_16x16x32_bf16 v[58:61], v[166:169], v[182:185], v[58:61]
	v_mfma_f32_16x16x32_bf16 v[50:53], v[174:177], v[182:185], v[50:53]
	v_mfma_f32_16x16x32_bf16 v[42:45], v[166:169], v[190:193], v[42:45]
	v_mfma_f32_16x16x32_bf16 v[34:37], v[174:177], v[190:193], v[34:37]
	v_mfma_f32_16x16x32_bf16 v[26:29], v[166:169], v[212:215], v[26:29]
	v_mfma_f32_16x16x32_bf16 v[18:21], v[174:177], v[212:215], v[18:21]
	v_mfma_f32_16x16x32_bf16 v[10:13], v[166:169], v[220:223], v[10:13]
	v_mfma_f32_16x16x32_bf16 v[2:5], v[174:177], v[220:223], v[2:5]
	v_mfma_f32_16x16x32_bf16 v[58:61], v[170:173], v[186:189], v[58:61]
	v_mfma_f32_16x16x32_bf16 v[50:53], v[178:181], v[186:189], v[50:53]
	v_mfma_f32_16x16x32_bf16 v[42:45], v[170:173], v[208:211], v[42:45]
	v_mfma_f32_16x16x32_bf16 v[34:37], v[178:181], v[208:211], v[34:37]
	v_mfma_f32_16x16x32_bf16 v[26:29], v[170:173], v[216:219], v[26:29]
	v_mfma_f32_16x16x32_bf16 v[18:21], v[178:181], v[216:219], v[18:21]
	v_mfma_f32_16x16x32_bf16 v[10:13], v[170:173], v[228:231], v[10:13]
	v_mfma_f32_16x16x32_bf16 v[2:5], v[178:181], v[228:231], v[2:5]
	s_setprio 0
	s_barrier
	s_add_i32 s17, 0, 0x18000
	s_add_i32 s28, 0, 0x1c000
	v_add_u32_e32 v162, s17, v148
	v_add_u32_e32 v178, s28, v148
	ds_read_b128 v[142:145], v162
	ds_read_b128 v[154:157], v162 offset:1024
	ds_read_b128 v[158:161], v162 offset:2048
	ds_read_b128 v[162:165], v162 offset:3072
	ds_read_b128 v[166:169], v178
	ds_read_b128 v[170:173], v178 offset:1024
	ds_read_b128 v[174:177], v178 offset:2048
	ds_read_b128 v[178:181], v178 offset:3072
	s_add_u32 s30, s34, s8
	s_addc_u32 s31, s35, s9
	s_mov_b32 m0, s67
	v_lshl_add_u64 v[240:241], s[30:31], 0, v[136:137]
	ds_read_b128 v[182:185], v153 offset:32768
	ds_read_b128 v[186:189], v153 offset:33792
	ds_read_b128 v[190:193], v153 offset:34816
	ds_read_b128 v[208:211], v153 offset:35840
	ds_read_b128 v[212:215], v153 offset:36864
	ds_read_b128 v[216:219], v153 offset:37888
	ds_read_b128 v[220:223], v153 offset:38912
	ds_read_b128 v[228:231], v153 offset:39936
	global_load_lds_dwordx4 v[240:241], off
	v_lshl_add_u64 v[240:241], s[30:31], 0, v[134:135]
	s_mov_b32 m0, s68
	s_nop 0
	global_load_lds_dwordx4 v[240:241], off
	s_waitcnt vmcnt(8)
	s_waitcnt lgkmcnt(0)
	s_barrier
	s_setprio 1
	s_waitcnt lgkmcnt(0)
	v_mfma_f32_16x16x32_bf16 v[124:127], v[142:145], v[182:185], v[124:127]
	v_mfma_f32_16x16x32_bf16 v[120:123], v[158:161], v[182:185], v[120:123]
	v_mfma_f32_16x16x32_bf16 v[112:115], v[142:145], v[190:193], v[112:115]
	v_mfma_f32_16x16x32_bf16 v[104:107], v[158:161], v[190:193], v[104:107]
	v_mfma_f32_16x16x32_bf16 v[94:97], v[142:145], v[212:215], v[94:97]
	v_mfma_f32_16x16x32_bf16 v[86:89], v[158:161], v[212:215], v[86:89]
	v_mfma_f32_16x16x32_bf16 v[78:81], v[142:145], v[220:223], v[78:81]
	v_mfma_f32_16x16x32_bf16 v[70:73], v[158:161], v[220:223], v[70:73]
	v_mfma_f32_16x16x32_bf16 v[124:127], v[154:157], v[186:189], v[124:127]
	v_mfma_f32_16x16x32_bf16 v[120:123], v[162:165], v[186:189], v[120:123]
	v_mfma_f32_16x16x32_bf16 v[112:115], v[154:157], v[208:211], v[112:115]
	v_mfma_f32_16x16x32_bf16 v[104:107], v[162:165], v[208:211], v[104:107]
	v_mfma_f32_16x16x32_bf16 v[94:97], v[154:157], v[216:219], v[94:97]
	v_mfma_f32_16x16x32_bf16 v[86:89], v[162:165], v[216:219], v[86:89]
	v_mfma_f32_16x16x32_bf16 v[78:81], v[154:157], v[228:231], v[78:81]
	v_mfma_f32_16x16x32_bf16 v[70:73], v[162:165], v[228:231], v[70:73]
	s_setprio 0
	s_setprio 1
	v_mfma_f32_16x16x32_bf16 v[128:131], v[166:169], v[182:185], v[128:131]
	v_mfma_f32_16x16x32_bf16 v[116:119], v[174:177], v[182:185], v[116:119]
	v_mfma_f32_16x16x32_bf16 v[108:111], v[166:169], v[190:193], v[108:111]
	v_mfma_f32_16x16x32_bf16 v[100:103], v[174:177], v[190:193], v[100:103]
	v_mfma_f32_16x16x32_bf16 v[90:93], v[166:169], v[212:215], v[90:93]
	v_mfma_f32_16x16x32_bf16 v[82:85], v[174:177], v[212:215], v[82:85]
	v_mfma_f32_16x16x32_bf16 v[74:77], v[166:169], v[220:223], v[74:77]
	v_mfma_f32_16x16x32_bf16 v[66:69], v[174:177], v[220:223], v[66:69]
	v_mfma_f32_16x16x32_bf16 v[128:131], v[170:173], v[186:189], v[128:131]
	v_mfma_f32_16x16x32_bf16 v[116:119], v[178:181], v[186:189], v[116:119]
	v_mfma_f32_16x16x32_bf16 v[108:111], v[170:173], v[208:211], v[108:111]
	v_mfma_f32_16x16x32_bf16 v[100:103], v[178:181], v[208:211], v[100:103]
	v_mfma_f32_16x16x32_bf16 v[90:93], v[170:173], v[216:219], v[90:93]
	v_mfma_f32_16x16x32_bf16 v[82:85], v[178:181], v[216:219], v[82:85]
	v_mfma_f32_16x16x32_bf16 v[74:77], v[170:173], v[228:231], v[74:77]
	v_mfma_f32_16x16x32_bf16 v[66:69], v[178:181], v[228:231], v[66:69]
	s_setprio 0
	s_barrier
; #define PG8_STAGE(bufoff, gbase, voff) do { _Pragma("unroll") for (int _i = 0; _i < 2; ++_i) \
;         __builtin_amdgcn_global_load_lds((const unsigned*)((const char*)(gbase) + (voff)[_i]), (PG8_LAS unsigned*)(lds + (bufoff) + ldsw + _i * 8192), 16, 0, 0); } while (0)
; #define PG8_LDA(dst, b, h) do { _Pragma("unroll") for (int m = 0; m < 4; ++m) _Pragma("unroll") for (int k = 0; k < 2; ++k) dst[m][k] = *(const PG8_LAS bf16x8*)(lds + PG8_SA(b, h) + aoff + m * 2048 + k * 1024); } while (0)
; #define PG8_MMA(ai, bj, At, Bt) do { __builtin_amdgcn_s_setprio(1); _Pragma("unroll") for (int m = 0; m < 4; ++m) _Pragma("unroll") for (int n = 0; n < 2; ++n) _Pragma("unroll") for (int k = 0; k < 2; ++k) \
;         acc[ai][bj][m][n] = __builtin_amdgcn_mfma_f32_16x16x32_bf16(Bt[n][k], At[m][k], acc[ai][bj][m][n], 0, 0, 0); __builtin_amdgcn_s_setprio(0); } while (0)
; #define PG8_WAIT_V(n) asm volatile("s_waitcnt vmcnt(" #n ")" ::: "memory")
; #define PG8_WAIT_L(n) asm volatile("s_waitcnt lgkmcnt(" #n ")" ::: "memory")
; #define PG8_BAR __builtin_amdgcn_s_barrier()
; #define PG8_SCHED __builtin_amdgcn_sched_barrier(0)
; template <class Epi, class Sched, bool ALIGN_EPI = false, bool SP2 = false>
; __device__ __forceinline__ void gemm_phase(PG8_LAS unsigned char* lds, const Gemm g, const Sched& S, const Epi& E) {
;     ...
;             PG8_LDA(At, 1, 1); PG8_STAGE(PG8_SB(1, 0), b3, voffB); PG8_STAGE(PG8_SB(1, 1), b3 + hstep, voffB); PG8_STAGE(PG8_SA(1, 0), a3, voffA);
;             PG8_WAIT_V(8); PG8_WAIT_L(0); PG8_BAR; PG8_MMA(1, 0, At, B0); PG8_MMA(1, 1, At, B1); PG8_BAR; PG8_SCHED;
	s_add_i32 s17, s17, s58
	v_lshl_add_u64 v[146:147], v[146:147], 0, s[24:25]
	s_mov_b32 m0, s17
	ds_read_b128 v[182:185], v153 offset:49152
	ds_read_b128 v[186:189], v153 offset:50176
	ds_read_b128 v[190:193], v153 offset:51200
	ds_read_b128 v[208:211], v153 offset:52224
	ds_read_b128 v[212:215], v153 offset:53248
	ds_read_b128 v[216:219], v153 offset:54272
	ds_read_b128 v[220:223], v153 offset:55296
	ds_read_b128 v[228:231], v153 offset:56320
	global_load_lds_dwordx4 v[146:147], off
	v_lshl_add_u64 v[146:147], v[224:225], 0, s[24:25]
	s_add_i32 m0, s17, 0x2000
	s_add_i32 s17, s28, s58
	global_load_lds_dwordx4 v[146:147], off
	v_lshl_add_u64 v[146:147], v[232:233], 0, s[24:25]
	s_mov_b32 m0, s17
	s_nop 0
	global_load_lds_dwordx4 v[146:147], off
	v_lshl_add_u64 v[146:147], v[234:235], 0, s[24:25]
	s_add_i32 m0, s17, 0x2000
	s_nop 0
	global_load_lds_dwordx4 v[146:147], off
	v_lshl_add_u64 v[146:147], v[236:237], 0, s[24:25]
	s_mov_b32 m0, s69
	s_nop 0
	global_load_lds_dwordx4 v[146:147], off
	v_lshl_add_u64 v[146:147], v[238:239], 0, s[24:25]
	s_mov_b32 m0, s70
	s_nop 0
	global_load_lds_dwordx4 v[146:147], off
	s_waitcnt vmcnt(8)
	s_waitcnt lgkmcnt(0)
	s_barrier
	s_setprio 1
	s_waitcnt lgkmcnt(0)
	v_mfma_f32_16x16x32_bf16 v[62:65], v[142:145], v[182:185], v[62:65]
	v_mfma_f32_16x16x32_bf16 v[54:57], v[158:161], v[182:185], v[54:57]
	v_mfma_f32_16x16x32_bf16 v[46:49], v[142:145], v[190:193], v[46:49]
	v_mfma_f32_16x16x32_bf16 v[38:41], v[158:161], v[190:193], v[38:41]
	v_mfma_f32_16x16x32_bf16 v[30:33], v[142:145], v[212:215], v[30:33]
	v_mfma_f32_16x16x32_bf16 v[22:25], v[158:161], v[212:215], v[22:25]
	v_mfma_f32_16x16x32_bf16 v[14:17], v[142:145], v[220:223], v[14:17]
	v_mfma_f32_16x16x32_bf16 v[6:9], v[158:161], v[220:223], v[6:9]
	v_mfma_f32_16x16x32_bf16 v[62:65], v[154:157], v[186:189], v[62:65]
	v_mfma_f32_16x16x32_bf16 v[54:57], v[162:165], v[186:189], v[54:57]
	v_mfma_f32_16x16x32_bf16 v[46:49], v[154:157], v[208:211], v[46:49]
	v_mfma_f32_16x16x32_bf16 v[38:41], v[162:165], v[208:211], v[38:41]
	v_mfma_f32_16x16x32_bf16 v[30:33], v[154:157], v[216:219], v[30:33]
	v_mfma_f32_16x16x32_bf16 v[22:25], v[162:165], v[216:219], v[22:25]
	v_mfma_f32_16x16x32_bf16 v[14:17], v[154:157], v[228:231], v[14:17]
	v_mfma_f32_16x16x32_bf16 v[6:9], v[162:165], v[228:231], v[6:9]
	s_setprio 0
	s_setprio 1
	v_mfma_f32_16x16x32_bf16 v[58:61], v[166:169], v[182:185], v[58:61]
	v_mfma_f32_16x16x32_bf16 v[50:53], v[174:177], v[182:185], v[50:53]
	v_mfma_f32_16x16x32_bf16 v[42:45], v[166:169], v[190:193], v[42:45]
	v_mfma_f32_16x16x32_bf16 v[34:37], v[174:177], v[190:193], v[34:37]
	v_mfma_f32_16x16x32_bf16 v[26:29], v[166:169], v[212:215], v[26:29]
	v_mfma_f32_16x16x32_bf16 v[18:21], v[174:177], v[212:215], v[18:21]
	v_mfma_f32_16x16x32_bf16 v[10:13], v[166:169], v[220:223], v[10:13]
	v_mfma_f32_16x16x32_bf16 v[2:5], v[174:177], v[220:223], v[2:5]
	v_mfma_f32_16x16x32_bf16 v[58:61], v[170:173], v[186:189], v[58:61]
	v_mfma_f32_16x16x32_bf16 v[50:53], v[178:181], v[186:189], v[50:53]
	v_mfma_f32_16x16x32_bf16 v[42:45], v[170:173], v[208:211], v[42:45]
	v_mfma_f32_16x16x32_bf16 v[34:37], v[178:181], v[208:211], v[34:37]
	v_mfma_f32_16x16x32_bf16 v[26:29], v[170:173], v[216:219], v[26:29]
	v_mfma_f32_16x16x32_bf16 v[18:21], v[178:181], v[216:219], v[18:21]
	v_mfma_f32_16x16x32_bf16 v[10:13], v[170:173], v[228:231], v[10:13]
	v_mfma_f32_16x16x32_bf16 v[2:5], v[178:181], v[228:231], v[2:5]
	s_setprio 0
	s_barrier
	s_add_u32 s2, s2, 0x100
	s_addc_u32 s3, s3, 0
	s_add_u32 s4, s4, 0x100
	s_addc_u32 s16, s16, 0
	s_cmp_ge_i32 s22, s71
	s_mov_b32 s17, s22
	s_cbranch_scc0 .LBB0_499

; __device__ __forceinline__ unsigned pk2(float lo, float hi) { f32x2 v = {lo, hi}; bf16x2_t b = __builtin_convertvector(v, bf16x2_t); return __builtin_bit_cast(unsigned, b); }
; __device__ __forceinline__ float ex2(float x) { return __builtin_amdgcn_exp2f(x); }
; __device__ __forceinline__ float rcpf_(float x) { return __builtin_amdgcn_rcpf(x); }
; __device__ __forceinline__ float ssf(const ssq_t* p) { return (float)(*p) * (1.0f / 1048576.0f); }
;     __device__ __forceinline__ void operator()(const f32x4 (&acc)[2][2][4][2], const pg8::Unit& u, int wr, int wc, int fr, int fq) const {
; #pragma unroll
;         for (int ai = 0; ai < 2; ++ai)
; #pragma unroll
;             for (int m = 0; m < 4; ++m) {
;                 const int row = u.pm * 256 + ai * 128 + wr * 64 + m * 16 + fr;
;                 const float r = rsqrtf(ssf(SSin + row) * (1.0f / D) + EPS);
;                 const int col = u.pn * 128 + wc * 32 + fq * 8;
;                 float v[8];
; #pragma unroll
;                 for (int n = 0; n < 2; ++n) {
;                     const f32x4 g = acc[ai][0][m][n] * r, up = acc[ai][1][m][n] * r;
; #pragma unroll
;                     for (int i = 0; i < 4; ++i) v[4 * n + i] = g[i] * rcpf_(1.0f + ex2(-g[i] * LOG2E)) * up[i];
;                 }
;                 u32x4 w; w.x = pk2(v[0], v[1]); w.y = pk2(v[2], v[3]); w.z = pk2(v[4], v[5]); w.w = pk2(v[6], v[7]);
;                 *(u32x4*)(O + (size_t)row * FF + col) = w;
;             }
.LBB0_502:
	s_lshl_b32 s2, s77, 8
	v_add_u32_e32 v190, s2, v1
	v_add_u32_e32 v192, s2, v149
	v_add_u32_e32 v208, s2, v150
	v_add_u32_e32 v210, s2, v151
	v_add_u32_e32 v212, 0x80, v190
	v_add_u32_e32 v214, 0x90, v190
	v_add_u32_e32 v216, 0xa0, v190
	v_add_u32_e32 v218, 0xb0, v190
	v_ashrrev_i32_e32 v191, 31, v190
	v_ashrrev_i32_e32 v193, 31, v192
	v_ashrrev_i32_e32 v209, 31, v208
	v_ashrrev_i32_e32 v211, 31, v210
	v_ashrrev_i32_e32 v213, 31, v212
	v_ashrrev_i32_e32 v215, 31, v214
	v_ashrrev_i32_e32 v217, 31, v216
	v_ashrrev_i32_e32 v219, 31, v218
	v_lshl_add_u64 v[220:221], v[190:191], 3, s[46:47]
	v_lshl_add_u64 v[222:223], v[192:193], 3, s[46:47]
	v_lshl_add_u64 v[224:225], v[208:209], 3, s[46:47]
	v_lshl_add_u64 v[228:229], v[210:211], 3, s[46:47]
	v_lshl_add_u64 v[230:231], v[212:213], 3, s[46:47]
	v_lshl_add_u64 v[232:233], v[214:215], 3, s[46:47]
	v_lshl_add_u64 v[234:235], v[216:217], 3, s[46:47]
	v_lshl_add_u64 v[236:237], v[218:219], 3, s[46:47]
	global_load_dwordx2 v[174:175], v[220:221], off
	global_load_dwordx2 v[176:177], v[222:223], off
	global_load_dwordx2 v[178:179], v[224:225], off
	global_load_dwordx2 v[180:181], v[228:229], off
	global_load_dwordx2 v[182:183], v[230:231], off
	global_load_dwordx2 v[184:185], v[232:233], off
	global_load_dwordx2 v[186:187], v[234:235], off
	global_load_dwordx2 v[188:189], v[236:237], off
	s_waitcnt vmcnt(0)
	v_add_u32_e32 v146, s2, v1
	v_ashrrev_i32_e32 v147, 31, v146
	v_lshl_add_u64 v[142:143], v[146:147], 3, s[46:47]
	s_nop 0
	v_lshl_or_b32 v154, s76, 7, v152
	v_ashrrev_i32_e32 v155, 31, v154
	v_mov_b64_e32 v[142:143], s[44:45]
	v_add_u32_e32 v156, s2, v149
	s_movk_i32 s1, 0x1600
	v_mad_i64_i32 v[158:159], s[16:17], v146, s1, v[142:143]
	s_nop 0
	v_ffbh_u32_e32 v147, v175
	v_min_u32_e32 v147, 32, v147
	v_lshlrev_b64 v[144:145], v147, v[174:175]
	v_min_u32_e32 v144, 1, v144
	v_or_b32_e32 v144, v145, v144
	v_cvt_f32_u32_e32 v157, v144
	v_sub_u32_e32 v147, 32, v147
	v_lshlrev_b64 v[144:145], 1, v[154:155]
	v_ldexp_f32 v147, v157, v147
	v_mul_f32_e32 v147, 0x35800000, v147
	v_fmamk_f32 v147, v147, 0x3a800000, v196
	v_mul_f32_e32 v154, 0x4b800000, v147
	v_cmp_gt_f32_e32 vcc, s23, v147
	v_ashrrev_i32_e32 v157, 31, v156
	s_nop 0
	v_cndmask_b32_e32 v147, v147, v154, vcc
	v_rsq_f32_e32 v147, v147
	v_lshl_add_u64 v[154:155], v[158:159], 0, v[144:145]
	v_lshl_add_u64 v[158:159], v[156:157], 3, s[46:47]
	v_mul_f32_e32 v157, 0x45800000, v147
	v_cndmask_b32_e32 v160, v147, v157, vcc
	v_pk_mul_f32 v[124:125], v[124:125], v[160:161] op_sel_hi:[1,0]
	v_pk_mul_f32 v[126:127], v[126:127], v[160:161] op_sel_hi:[1,0]
	v_pk_mul_f32 v[120:121], v[120:121], v[160:161] op_sel_hi:[1,0]
	v_pk_mul_f32 v[122:123], v[122:123], v[160:161] op_sel_hi:[1,0]
	v_pk_mul_f32 v[128:129], v[128:129], v[160:161] op_sel_hi:[1,0]
	v_pk_mul_f32 v[130:131], v[130:131], v[160:161] op_sel_hi:[1,0]
	v_pk_mul_f32 v[116:117], v[116:117], v[160:161] op_sel_hi:[1,0]
	v_pk_mul_f32 v[118:119], v[118:119], v[160:161] op_sel_hi:[1,0]
	v_mul_f32_e32 v147, 0xbfb8aa3b, v124
	v_mul_f32_e32 v157, 0xbfb8aa3b, v125
	v_mul_f32_e32 v160, 0xbfb8aa3b, v126
	v_mul_f32_e32 v161, 0xbfb8aa3b, v127
	v_mul_f32_e32 v162, 0xbfb8aa3b, v120
	v_mul_f32_e32 v163, 0xbfb8aa3b, v121
	v_mul_f32_e32 v164, 0xbfb8aa3b, v122
	v_mul_f32_e32 v165, 0xbfb8aa3b, v123
	v_exp_f32_e32 v147, v147
	v_exp_f32_e32 v157, v157
	v_exp_f32_e32 v160, v160
	v_exp_f32_e32 v161, v161
	v_exp_f32_e32 v162, v162
	v_exp_f32_e32 v163, v163
	v_exp_f32_e32 v164, v164
	v_exp_f32_e32 v165, v165
	v_add_f32_e32 v147, 1.0, v147
	v_add_f32_e32 v157, 1.0, v157
	v_add_f32_e32 v166, 1.0, v160
	v_add_f32_e32 v167, 1.0, v161
	v_add_f32_e32 v168, 1.0, v162
	v_add_f32_e32 v169, 1.0, v163
	v_add_f32_e32 v170, 1.0, v164
	v_add_f32_e32 v171, 1.0, v165
	v_rcp_f32_e32 v160, v147
	v_rcp_f32_e32 v161, v157
	v_rcp_f32_e32 v162, v166
	v_rcp_f32_e32 v163, v167
	v_rcp_f32_e32 v164, v168
	v_rcp_f32_e32 v165, v169
	v_rcp_f32_e32 v166, v170
	v_rcp_f32_e32 v167, v171
	v_pk_mul_f32 v[124:125], v[124:125], v[160:161]
	v_pk_mul_f32 v[126:127], v[126:127], v[162:163]
	v_pk_mul_f32 v[120:121], v[120:121], v[164:165]
	v_pk_mul_f32 v[122:123], v[122:123], v[166:167]
	v_pk_mul_f32 v[124:125], v[128:129], v[124:125]
	v_pk_mul_f32 v[126:127], v[130:131], v[126:127]
	v_pk_mul_f32 v[120:121], v[116:117], v[120:121]
	v_pk_mul_f32 v[122:123], v[118:119], v[122:123]
	v_cvt_pk_bf16_f32 v116, v124, v125
	v_cvt_pk_bf16_f32 v117, v126, v127
	v_cvt_pk_bf16_f32 v118, v120, v121
	v_cvt_pk_bf16_f32 v119, v122, v123
	global_store_dwordx4 v[154:155], v[116:119], off
	s_nop 0
	s_nop 0
	v_add_u32_e32 v118, s2, v150
	s_nop 0
	v_ffbh_u32_e32 v119, v177
	v_min_u32_e32 v119, 32, v119
	v_lshlrev_b64 v[116:117], v119, v[176:177]
	v_min_u32_e32 v116, 1, v116
	v_or_b32_e32 v116, v117, v116
	v_cvt_f32_u32_e32 v120, v116
	v_sub_u32_e32 v119, 32, v119
	v_mad_i64_i32 v[116:117], s[16:17], v156, s1, v[142:143]
	v_ldexp_f32 v119, v120, v119
	v_mul_f32_e32 v119, 0x35800000, v119
	v_fmamk_f32 v119, v119, 0x3a800000, v196
	v_mul_f32_e32 v120, 0x4b800000, v119
	v_cmp_gt_f32_e32 vcc, s23, v119
	v_lshl_add_u64 v[116:117], v[116:117], 0, v[144:145]
	s_nop 0
	v_cndmask_b32_e32 v119, v119, v120, vcc
	v_rsq_f32_e32 v122, v119
	v_ashrrev_i32_e32 v119, 31, v118
	v_lshl_add_u64 v[120:121], v[118:119], 3, s[46:47]
	v_mul_f32_e32 v119, 0x45800000, v122
	v_cndmask_b32_e32 v122, v122, v119, vcc
	v_pk_mul_f32 v[112:113], v[112:113], v[122:123] op_sel_hi:[1,0]
	v_pk_mul_f32 v[114:115], v[114:115], v[122:123] op_sel_hi:[1,0]
	v_pk_mul_f32 v[104:105], v[104:105], v[122:123] op_sel_hi:[1,0]
	v_pk_mul_f32 v[106:107], v[106:107], v[122:123] op_sel_hi:[1,0]
; __device__ __forceinline__ unsigned pk2(float lo, float hi) { f32x2 v = {lo, hi}; bf16x2_t b = __builtin_convertvector(v, bf16x2_t); return __builtin_bit_cast(unsigned, b); }
; __device__ __forceinline__ float ex2(float x) { return __builtin_amdgcn_exp2f(x); }
; __device__ __forceinline__ float rcpf_(float x) { return __builtin_amdgcn_rcpf(x); }
; __device__ __forceinline__ float ssf(const ssq_t* p) { return (float)(*p) * (1.0f / 1048576.0f); }
;     __device__ __forceinline__ void operator()(const f32x4 (&acc)[2][2][4][2], const pg8::Unit& u, int wr, int wc, int fr, int fq) const {
; #pragma unroll
;         for (int ai = 0; ai < 2; ++ai)
; #pragma unroll
;             for (int m = 0; m < 4; ++m) {
;                 const int row = u.pm * 256 + ai * 128 + wr * 64 + m * 16 + fr;
;                 const float r = rsqrtf(ssf(SSin + row) * (1.0f / D) + EPS);
;                 const int col = u.pn * 128 + wc * 32 + fq * 8;
;                 float v[8];
; #pragma unroll
;                 for (int n = 0; n < 2; ++n) {
;                     const f32x4 g = acc[ai][0][m][n] * r, up = acc[ai][1][m][n] * r;
; #pragma unroll
;                     for (int i = 0; i < 4; ++i) v[4 * n + i] = g[i] * rcpf_(1.0f + ex2(-g[i] * LOG2E)) * up[i];
;                 }
;                 u32x4 w; w.x = pk2(v[0], v[1]); w.y = pk2(v[2], v[3]); w.z = pk2(v[4], v[5]); w.w = pk2(v[6], v[7]);
;                 *(u32x4*)(O + (size_t)row * FF + col) = w;
;             }
	v_pk_mul_f32 v[108:109], v[108:109], v[122:123] op_sel_hi:[1,0]
	v_pk_mul_f32 v[110:111], v[110:111], v[122:123] op_sel_hi:[1,0]
	v_pk_mul_f32 v[100:101], v[100:101], v[122:123] op_sel_hi:[1,0]
	v_pk_mul_f32 v[102:103], v[102:103], v[122:123] op_sel_hi:[1,0]
	v_mul_f32_e32 v119, 0xbfb8aa3b, v112
	v_mul_f32_e32 v122, 0xbfb8aa3b, v113
	v_mul_f32_e32 v123, 0xbfb8aa3b, v114
	v_mul_f32_e32 v124, 0xbfb8aa3b, v115
	v_mul_f32_e32 v125, 0xbfb8aa3b, v104
	v_mul_f32_e32 v126, 0xbfb8aa3b, v105
	v_mul_f32_e32 v127, 0xbfb8aa3b, v106
	v_mul_f32_e32 v128, 0xbfb8aa3b, v107
	v_exp_f32_e32 v119, v119
	v_exp_f32_e32 v122, v122
	v_exp_f32_e32 v123, v123
	v_exp_f32_e32 v124, v124
	v_exp_f32_e32 v125, v125
	v_exp_f32_e32 v126, v126
	v_exp_f32_e32 v127, v127
	v_exp_f32_e32 v128, v128
	v_add_f32_e32 v119, 1.0, v119
	v_add_f32_e32 v129, 1.0, v122
	v_add_f32_e32 v130, 1.0, v123
	v_add_f32_e32 v131, 1.0, v124
	v_add_f32_e32 v147, 1.0, v125
	v_add_f32_e32 v154, 1.0, v126
	v_add_f32_e32 v155, 1.0, v127
	v_add_f32_e32 v156, 1.0, v128
	v_rcp_f32_e32 v122, v119
	v_rcp_f32_e32 v123, v129
	v_rcp_f32_e32 v124, v130
	v_rcp_f32_e32 v125, v131
	v_rcp_f32_e32 v126, v147
	v_rcp_f32_e32 v127, v154
	v_rcp_f32_e32 v128, v155
	v_rcp_f32_e32 v129, v156
	v_pk_mul_f32 v[112:113], v[112:113], v[122:123]
	v_pk_mul_f32 v[114:115], v[114:115], v[124:125]
	v_pk_mul_f32 v[104:105], v[104:105], v[126:127]
	v_pk_mul_f32 v[106:107], v[106:107], v[128:129]
	v_pk_mul_f32 v[108:109], v[108:109], v[112:113]
	v_pk_mul_f32 v[110:111], v[110:111], v[114:115]
	v_pk_mul_f32 v[104:105], v[100:101], v[104:105]
	v_pk_mul_f32 v[106:107], v[102:103], v[106:107]
	v_cvt_pk_bf16_f32 v100, v108, v109
	v_cvt_pk_bf16_f32 v101, v110, v111
	v_cvt_pk_bf16_f32 v102, v104, v105
	v_cvt_pk_bf16_f32 v103, v106, v107
	global_store_dwordx4 v[116:117], v[100:103], off
	s_nop 0
	s_nop 0
	v_add_u32_e32 v102, s2, v151
	s_nop 0
	v_ffbh_u32_e32 v103, v179
	v_min_u32_e32 v103, 32, v103
	v_lshlrev_b64 v[100:101], v103, v[178:179]
	v_min_u32_e32 v100, 1, v100
	v_or_b32_e32 v100, v101, v100
	v_cvt_f32_u32_e32 v104, v100
	v_sub_u32_e32 v103, 32, v103
	v_mad_i64_i32 v[100:101], s[2:3], v118, s1, v[142:143]
	v_ldexp_f32 v103, v104, v103
	v_mul_f32_e32 v103, 0x35800000, v103
	v_fmamk_f32 v103, v103, 0x3a800000, v196
	v_mul_f32_e32 v104, 0x4b800000, v103
	v_cmp_gt_f32_e32 vcc, s23, v103
	v_lshl_add_u64 v[100:101], v[100:101], 0, v[144:145]
	s_nop 0
	v_cndmask_b32_e32 v103, v103, v104, vcc
	v_rsq_f32_e32 v106, v103
	v_ashrrev_i32_e32 v103, 31, v102
	v_lshl_add_u64 v[104:105], v[102:103], 3, s[46:47]
	v_mul_f32_e32 v103, 0x45800000, v106
	v_cndmask_b32_e32 v106, v106, v103, vcc
	v_pk_mul_f32 v[94:95], v[94:95], v[106:107] op_sel_hi:[1,0]
	v_pk_mul_f32 v[96:97], v[96:97], v[106:107] op_sel_hi:[1,0]
	v_pk_mul_f32 v[86:87], v[86:87], v[106:107] op_sel_hi:[1,0]
	v_pk_mul_f32 v[88:89], v[88:89], v[106:107] op_sel_hi:[1,0]
	v_pk_mul_f32 v[90:91], v[90:91], v[106:107] op_sel_hi:[1,0]
	v_pk_mul_f32 v[92:93], v[92:93], v[106:107] op_sel_hi:[1,0]
	v_pk_mul_f32 v[82:83], v[82:83], v[106:107] op_sel_hi:[1,0]
	v_pk_mul_f32 v[84:85], v[84:85], v[106:107] op_sel_hi:[1,0]
	v_mul_f32_e32 v103, 0xbfb8aa3b, v94
	v_mul_f32_e32 v106, 0xbfb8aa3b, v95
	v_mul_f32_e32 v107, 0xbfb8aa3b, v96
	v_mul_f32_e32 v108, 0xbfb8aa3b, v97
	v_mul_f32_e32 v109, 0xbfb8aa3b, v86
	v_mul_f32_e32 v110, 0xbfb8aa3b, v87
	v_mul_f32_e32 v111, 0xbfb8aa3b, v88
	v_mul_f32_e32 v112, 0xbfb8aa3b, v89
	v_exp_f32_e32 v103, v103
	v_exp_f32_e32 v106, v106
	v_exp_f32_e32 v107, v107
	v_exp_f32_e32 v108, v108
	v_exp_f32_e32 v109, v109
	v_exp_f32_e32 v110, v110
	v_exp_f32_e32 v111, v111
	v_exp_f32_e32 v112, v112
	v_add_f32_e32 v103, 1.0, v103
	v_add_f32_e32 v113, 1.0, v106
	v_add_f32_e32 v114, 1.0, v107
	v_add_f32_e32 v115, 1.0, v108
	v_add_f32_e32 v116, 1.0, v109
	v_add_f32_e32 v117, 1.0, v110
	v_add_f32_e32 v118, 1.0, v111
	v_add_f32_e32 v119, 1.0, v112
	v_rcp_f32_e32 v106, v103
	v_rcp_f32_e32 v107, v113
	v_rcp_f32_e32 v108, v114
	v_rcp_f32_e32 v109, v115
	v_rcp_f32_e32 v110, v116
	v_rcp_f32_e32 v111, v117
	v_rcp_f32_e32 v112, v118
	v_rcp_f32_e32 v113, v119
	v_pk_mul_f32 v[94:95], v[94:95], v[106:107]
	v_pk_mul_f32 v[96:97], v[96:97], v[108:109]
	v_pk_mul_f32 v[86:87], v[86:87], v[110:111]
	v_pk_mul_f32 v[88:89], v[88:89], v[112:113]
	v_pk_mul_f32 v[90:91], v[90:91], v[94:95]
	v_pk_mul_f32 v[92:93], v[92:93], v[96:97]
	v_pk_mul_f32 v[86:87], v[82:83], v[86:87]
	v_pk_mul_f32 v[88:89], v[84:85], v[88:89]
	v_cvt_pk_bf16_f32 v82, v90, v91
	v_cvt_pk_bf16_f32 v83, v92, v93
	v_cvt_pk_bf16_f32 v84, v86, v87
	v_cvt_pk_bf16_f32 v85, v88, v89
	global_store_dwordx4 v[100:101], v[82:85], off
	s_nop 0
	s_nop 0
	v_ffbh_u32_e32 v84, v181
	v_min_u32_e32 v85, 32, v84
	v_lshlrev_b64 v[82:83], v85, v[180:181]
	v_min_u32_e32 v82, 1, v82
	v_or_b32_e32 v82, v83, v82
	v_cvt_f32_u32_e32 v86, v82
	v_sub_u32_e32 v85, 32, v85
	v_add_u32_e32 v84, 0x80, v146
	v_mad_i64_i32 v[82:83], s[2:3], v102, s1, v[142:143]
	v_ldexp_f32 v85, v86, v85
	v_mul_f32_e32 v85, 0x35800000, v85
	v_fmamk_f32 v85, v85, 0x3a800000, v196
	v_mul_f32_e32 v86, 0x4b800000, v85
	v_cmp_gt_f32_e32 vcc, s23, v85
	v_lshl_add_u64 v[82:83], v[82:83], 0, v[144:145]
	s_nop 0
	v_cndmask_b32_e32 v85, v85, v86, vcc
	v_rsq_f32_e32 v88, v85
	v_ashrrev_i32_e32 v85, 31, v84
	v_lshl_add_u64 v[86:87], v[84:85], 3, s[46:47]
	v_mul_f32_e32 v85, 0x45800000, v88
	v_cndmask_b32_e32 v88, v88, v85, vcc
	v_pk_mul_f32 v[78:79], v[78:79], v[88:89] op_sel_hi:[1,0]
	v_pk_mul_f32 v[80:81], v[80:81], v[88:89] op_sel_hi:[1,0]
	v_pk_mul_f32 v[70:71], v[70:71], v[88:89] op_sel_hi:[1,0]
	v_pk_mul_f32 v[72:73], v[72:73], v[88:89] op_sel_hi:[1,0]
	v_pk_mul_f32 v[74:75], v[74:75], v[88:89] op_sel_hi:[1,0]
; __device__ __forceinline__ unsigned pk2(float lo, float hi) { f32x2 v = {lo, hi}; bf16x2_t b = __builtin_convertvector(v, bf16x2_t); return __builtin_bit_cast(unsigned, b); }
; __device__ __forceinline__ float ex2(float x) { return __builtin_amdgcn_exp2f(x); }
; __device__ __forceinline__ float rcpf_(float x) { return __builtin_amdgcn_rcpf(x); }
; __device__ __forceinline__ float ssf(const ssq_t* p) { return (float)(*p) * (1.0f / 1048576.0f); }
;     __device__ __forceinline__ void operator()(const f32x4 (&acc)[2][2][4][2], const pg8::Unit& u, int wr, int wc, int fr, int fq) const {
; #pragma unroll
;         for (int ai = 0; ai < 2; ++ai)
; #pragma unroll
;             for (int m = 0; m < 4; ++m) {
;                 const int row = u.pm * 256 + ai * 128 + wr * 64 + m * 16 + fr;
;                 const float r = rsqrtf(ssf(SSin + row) * (1.0f / D) + EPS);
;                 const int col = u.pn * 128 + wc * 32 + fq * 8;
;                 float v[8];
; #pragma unroll
;                 for (int n = 0; n < 2; ++n) {
;                     const f32x4 g = acc[ai][0][m][n] * r, up = acc[ai][1][m][n] * r;
; #pragma unroll
;                     for (int i = 0; i < 4; ++i) v[4 * n + i] = g[i] * rcpf_(1.0f + ex2(-g[i] * LOG2E)) * up[i];
;                 }
;                 u32x4 w; w.x = pk2(v[0], v[1]); w.y = pk2(v[2], v[3]); w.z = pk2(v[4], v[5]); w.w = pk2(v[6], v[7]);
;                 *(u32x4*)(O + (size_t)row * FF + col) = w;
;             }
	v_pk_mul_f32 v[76:77], v[76:77], v[88:89] op_sel_hi:[1,0]
	v_pk_mul_f32 v[66:67], v[66:67], v[88:89] op_sel_hi:[1,0]
	v_pk_mul_f32 v[68:69], v[68:69], v[88:89] op_sel_hi:[1,0]
	v_mul_f32_e32 v85, 0xbfb8aa3b, v78
	v_mul_f32_e32 v88, 0xbfb8aa3b, v79
	v_mul_f32_e32 v89, 0xbfb8aa3b, v80
	v_mul_f32_e32 v90, 0xbfb8aa3b, v81
	v_mul_f32_e32 v91, 0xbfb8aa3b, v70
	v_mul_f32_e32 v92, 0xbfb8aa3b, v71
	v_mul_f32_e32 v93, 0xbfb8aa3b, v72
	v_mul_f32_e32 v94, 0xbfb8aa3b, v73
	v_exp_f32_e32 v85, v85
	v_exp_f32_e32 v88, v88
	v_exp_f32_e32 v89, v89
	v_exp_f32_e32 v90, v90
	v_exp_f32_e32 v91, v91
	v_exp_f32_e32 v92, v92
	v_exp_f32_e32 v93, v93
	v_exp_f32_e32 v94, v94
	v_add_f32_e32 v85, 1.0, v85
	v_add_f32_e32 v95, 1.0, v88
	v_add_f32_e32 v96, 1.0, v89
	v_add_f32_e32 v97, 1.0, v90
	v_add_f32_e32 v100, 1.0, v91
	v_add_f32_e32 v101, 1.0, v92
	v_add_f32_e32 v102, 1.0, v93
	v_add_f32_e32 v103, 1.0, v94
	v_rcp_f32_e32 v88, v85
	v_rcp_f32_e32 v89, v95
	v_rcp_f32_e32 v90, v96
	v_rcp_f32_e32 v91, v97
	v_rcp_f32_e32 v92, v100
	v_rcp_f32_e32 v93, v101
	v_rcp_f32_e32 v94, v102
	v_rcp_f32_e32 v95, v103
	v_pk_mul_f32 v[78:79], v[78:79], v[88:89]
	v_pk_mul_f32 v[80:81], v[80:81], v[90:91]
	v_pk_mul_f32 v[70:71], v[70:71], v[92:93]
	v_pk_mul_f32 v[72:73], v[72:73], v[94:95]
	v_pk_mul_f32 v[74:75], v[74:75], v[78:79]
	v_pk_mul_f32 v[76:77], v[76:77], v[80:81]
	v_pk_mul_f32 v[70:71], v[66:67], v[70:71]
	v_pk_mul_f32 v[72:73], v[68:69], v[72:73]
	v_cvt_pk_bf16_f32 v66, v74, v75
	v_cvt_pk_bf16_f32 v67, v76, v77
	v_cvt_pk_bf16_f32 v68, v70, v71
	v_cvt_pk_bf16_f32 v69, v72, v73
	global_store_dwordx4 v[82:83], v[66:69], off
	s_nop 0
	s_nop 0
	v_add_u32_e32 v68, 0x90, v146
	s_nop 0
	v_ffbh_u32_e32 v69, v183
	v_min_u32_e32 v69, 32, v69
	v_lshlrev_b64 v[66:67], v69, v[182:183]
	v_min_u32_e32 v66, 1, v66
	v_or_b32_e32 v66, v67, v66
	v_cvt_f32_u32_e32 v70, v66
	v_sub_u32_e32 v69, 32, v69
	v_mad_i64_i32 v[66:67], s[2:3], v84, s1, v[142:143]
	v_ldexp_f32 v69, v70, v69
	v_mul_f32_e32 v69, 0x35800000, v69
	v_fmamk_f32 v69, v69, 0x3a800000, v196
	v_mul_f32_e32 v70, 0x4b800000, v69
	v_cmp_gt_f32_e32 vcc, s23, v69
	v_lshl_add_u64 v[66:67], v[66:67], 0, v[144:145]
	s_nop 0
	v_cndmask_b32_e32 v69, v69, v70, vcc
	v_rsq_f32_e32 v72, v69
	v_ashrrev_i32_e32 v69, 31, v68
	v_lshl_add_u64 v[70:71], v[68:69], 3, s[46:47]
	v_mul_f32_e32 v69, 0x45800000, v72
	v_cndmask_b32_e32 v72, v72, v69, vcc
	v_pk_mul_f32 v[62:63], v[62:63], v[72:73] op_sel_hi:[1,0]
	v_pk_mul_f32 v[64:65], v[64:65], v[72:73] op_sel_hi:[1,0]
	v_pk_mul_f32 v[54:55], v[54:55], v[72:73] op_sel_hi:[1,0]
	v_pk_mul_f32 v[56:57], v[56:57], v[72:73] op_sel_hi:[1,0]
	v_pk_mul_f32 v[58:59], v[58:59], v[72:73] op_sel_hi:[1,0]
	v_pk_mul_f32 v[60:61], v[60:61], v[72:73] op_sel_hi:[1,0]
	v_pk_mul_f32 v[50:51], v[50:51], v[72:73] op_sel_hi:[1,0]
	v_pk_mul_f32 v[52:53], v[52:53], v[72:73] op_sel_hi:[1,0]
	v_mul_f32_e32 v69, 0xbfb8aa3b, v62
	v_mul_f32_e32 v72, 0xbfb8aa3b, v63
	v_mul_f32_e32 v73, 0xbfb8aa3b, v64
	v_mul_f32_e32 v74, 0xbfb8aa3b, v65
	v_mul_f32_e32 v75, 0xbfb8aa3b, v54
	v_mul_f32_e32 v76, 0xbfb8aa3b, v55
	v_mul_f32_e32 v77, 0xbfb8aa3b, v56
	v_mul_f32_e32 v78, 0xbfb8aa3b, v57
	v_exp_f32_e32 v69, v69
	v_exp_f32_e32 v72, v72
	v_exp_f32_e32 v73, v73
	v_exp_f32_e32 v74, v74
	v_exp_f32_e32 v75, v75
	v_exp_f32_e32 v76, v76
	v_exp_f32_e32 v77, v77
	v_exp_f32_e32 v78, v78
	v_add_f32_e32 v69, 1.0, v69
	v_add_f32_e32 v79, 1.0, v72
	v_add_f32_e32 v80, 1.0, v73
	v_add_f32_e32 v81, 1.0, v74
	v_add_f32_e32 v82, 1.0, v75
	v_add_f32_e32 v83, 1.0, v76
	v_add_f32_e32 v84, 1.0, v77
	v_add_f32_e32 v85, 1.0, v78
	v_rcp_f32_e32 v72, v69
	v_rcp_f32_e32 v73, v79
	v_rcp_f32_e32 v74, v80
	v_rcp_f32_e32 v75, v81
	v_rcp_f32_e32 v76, v82
	v_rcp_f32_e32 v77, v83
	v_rcp_f32_e32 v78, v84
	v_rcp_f32_e32 v79, v85
	v_pk_mul_f32 v[62:63], v[62:63], v[72:73]
	v_pk_mul_f32 v[64:65], v[64:65], v[74:75]
	v_pk_mul_f32 v[54:55], v[54:55], v[76:77]
	v_pk_mul_f32 v[56:57], v[56:57], v[78:79]
	v_pk_mul_f32 v[58:59], v[58:59], v[62:63]
	v_pk_mul_f32 v[60:61], v[60:61], v[64:65]
	v_pk_mul_f32 v[54:55], v[50:51], v[54:55]
	v_pk_mul_f32 v[56:57], v[52:53], v[56:57]
	v_cvt_pk_bf16_f32 v50, v58, v59
	v_cvt_pk_bf16_f32 v51, v60, v61
	v_cvt_pk_bf16_f32 v52, v54, v55
	v_cvt_pk_bf16_f32 v53, v56, v57
	global_store_dwordx4 v[66:67], v[50:53], off
	s_nop 0
	s_nop 0
	v_add_u32_e32 v52, 0xa0, v146
	s_nop 0
	v_ffbh_u32_e32 v53, v185
	v_min_u32_e32 v53, 32, v53
	v_lshlrev_b64 v[50:51], v53, v[184:185]
	v_min_u32_e32 v50, 1, v50
	v_or_b32_e32 v50, v51, v50
	v_cvt_f32_u32_e32 v54, v50
	v_sub_u32_e32 v53, 32, v53
	v_mad_i64_i32 v[50:51], s[2:3], v68, s1, v[142:143]
	v_ldexp_f32 v53, v54, v53
	v_mul_f32_e32 v53, 0x35800000, v53
	v_fmamk_f32 v53, v53, 0x3a800000, v196
	v_mul_f32_e32 v54, 0x4b800000, v53
	v_cmp_gt_f32_e32 vcc, s23, v53
	v_lshl_add_u64 v[50:51], v[50:51], 0, v[144:145]
	s_nop 0
	v_cndmask_b32_e32 v53, v53, v54, vcc
	v_rsq_f32_e32 v56, v53
	v_ashrrev_i32_e32 v53, 31, v52
	v_lshl_add_u64 v[54:55], v[52:53], 3, s[46:47]
	v_mul_f32_e32 v53, 0x45800000, v56
	v_cndmask_b32_e32 v56, v56, v53, vcc
	v_pk_mul_f32 v[46:47], v[46:47], v[56:57] op_sel_hi:[1,0]
	v_pk_mul_f32 v[48:49], v[48:49], v[56:57] op_sel_hi:[1,0]
	v_pk_mul_f32 v[38:39], v[38:39], v[56:57] op_sel_hi:[1,0]
	v_pk_mul_f32 v[40:41], v[40:41], v[56:57] op_sel_hi:[1,0]
	v_pk_mul_f32 v[42:43], v[42:43], v[56:57] op_sel_hi:[1,0]
	v_pk_mul_f32 v[44:45], v[44:45], v[56:57] op_sel_hi:[1,0]
	v_pk_mul_f32 v[34:35], v[34:35], v[56:57] op_sel_hi:[1,0]
	v_pk_mul_f32 v[36:37], v[36:37], v[56:57] op_sel_hi:[1,0]
	v_mul_f32_e32 v53, 0xbfb8aa3b, v46
	v_mul_f32_e32 v56, 0xbfb8aa3b, v47
	v_mul_f32_e32 v57, 0xbfb8aa3b, v48
	v_mul_f32_e32 v58, 0xbfb8aa3b, v49
; __device__ __forceinline__ unsigned pk2(float lo, float hi) { f32x2 v = {lo, hi}; bf16x2_t b = __builtin_convertvector(v, bf16x2_t); return __builtin_bit_cast(unsigned, b); }
; __device__ __forceinline__ float ex2(float x) { return __builtin_amdgcn_exp2f(x); }
; __device__ __forceinline__ float rcpf_(float x) { return __builtin_amdgcn_rcpf(x); }
; __device__ __forceinline__ float ssf(const ssq_t* p) { return (float)(*p) * (1.0f / 1048576.0f); }
;     __device__ __forceinline__ void operator()(const f32x4 (&acc)[2][2][4][2], const pg8::Unit& u, int wr, int wc, int fr, int fq) const {
; #pragma unroll
;         for (int ai = 0; ai < 2; ++ai)
; #pragma unroll
;             for (int m = 0; m < 4; ++m) {
;                 const int row = u.pm * 256 + ai * 128 + wr * 64 + m * 16 + fr;
;                 const float r = rsqrtf(ssf(SSin + row) * (1.0f / D) + EPS);
;                 const int col = u.pn * 128 + wc * 32 + fq * 8;
;                 float v[8];
; #pragma unroll
;                 for (int n = 0; n < 2; ++n) {
;                     const f32x4 g = acc[ai][0][m][n] * r, up = acc[ai][1][m][n] * r;
; #pragma unroll
;                     for (int i = 0; i < 4; ++i) v[4 * n + i] = g[i] * rcpf_(1.0f + ex2(-g[i] * LOG2E)) * up[i];
;                 }
;                 u32x4 w; w.x = pk2(v[0], v[1]); w.y = pk2(v[2], v[3]); w.z = pk2(v[4], v[5]); w.w = pk2(v[6], v[7]);
;                 *(u32x4*)(O + (size_t)row * FF + col) = w;
;             }
	v_mul_f32_e32 v59, 0xbfb8aa3b, v38
	v_mul_f32_e32 v60, 0xbfb8aa3b, v39
	v_mul_f32_e32 v61, 0xbfb8aa3b, v40
	v_mul_f32_e32 v62, 0xbfb8aa3b, v41
	v_exp_f32_e32 v53, v53
	v_exp_f32_e32 v56, v56
	v_exp_f32_e32 v57, v57
	v_exp_f32_e32 v58, v58
	v_exp_f32_e32 v59, v59
	v_exp_f32_e32 v60, v60
	v_exp_f32_e32 v61, v61
	v_exp_f32_e32 v62, v62
	v_add_f32_e32 v53, 1.0, v53
	v_add_f32_e32 v63, 1.0, v56
	v_add_f32_e32 v64, 1.0, v57
	v_add_f32_e32 v65, 1.0, v58
	v_add_f32_e32 v66, 1.0, v59
	v_add_f32_e32 v67, 1.0, v60
	v_add_f32_e32 v68, 1.0, v61
	v_add_f32_e32 v69, 1.0, v62
	v_rcp_f32_e32 v56, v53
	v_rcp_f32_e32 v57, v63
	v_rcp_f32_e32 v58, v64
	v_rcp_f32_e32 v59, v65
	v_rcp_f32_e32 v60, v66
	v_rcp_f32_e32 v61, v67
	v_rcp_f32_e32 v62, v68
	v_rcp_f32_e32 v63, v69
	v_pk_mul_f32 v[46:47], v[46:47], v[56:57]
	v_pk_mul_f32 v[48:49], v[48:49], v[58:59]
	v_pk_mul_f32 v[38:39], v[38:39], v[60:61]
	v_pk_mul_f32 v[40:41], v[40:41], v[62:63]
	v_pk_mul_f32 v[42:43], v[42:43], v[46:47]
	v_pk_mul_f32 v[44:45], v[44:45], v[48:49]
	v_pk_mul_f32 v[38:39], v[34:35], v[38:39]
	v_pk_mul_f32 v[40:41], v[36:37], v[40:41]
	v_cvt_pk_bf16_f32 v34, v42, v43
	v_cvt_pk_bf16_f32 v35, v44, v45
	v_cvt_pk_bf16_f32 v36, v38, v39
	v_cvt_pk_bf16_f32 v37, v40, v41
	global_store_dwordx4 v[50:51], v[34:37], off
	s_nop 0
	s_nop 0
	v_add_u32_e32 v36, 0xb0, v146
	s_nop 0
	v_ffbh_u32_e32 v37, v187
	v_min_u32_e32 v37, 32, v37
	v_lshlrev_b64 v[34:35], v37, v[186:187]
	v_min_u32_e32 v34, 1, v34
	v_or_b32_e32 v34, v35, v34
	v_cvt_f32_u32_e32 v38, v34
	v_sub_u32_e32 v37, 32, v37
	v_mad_i64_i32 v[34:35], s[2:3], v52, s1, v[142:143]
	v_ldexp_f32 v37, v38, v37
	v_mul_f32_e32 v37, 0x35800000, v37
	v_fmamk_f32 v37, v37, 0x3a800000, v196
	v_mul_f32_e32 v38, 0x4b800000, v37
	v_cmp_gt_f32_e32 vcc, s23, v37
	v_lshl_add_u64 v[34:35], v[34:35], 0, v[144:145]
	s_nop 0
	v_cndmask_b32_e32 v37, v37, v38, vcc
	v_rsq_f32_e32 v40, v37
	v_ashrrev_i32_e32 v37, 31, v36
	v_lshl_add_u64 v[38:39], v[36:37], 3, s[46:47]
	v_mul_f32_e32 v37, 0x45800000, v40
	v_cndmask_b32_e32 v40, v40, v37, vcc
	v_pk_mul_f32 v[30:31], v[30:31], v[40:41] op_sel_hi:[1,0]
	v_pk_mul_f32 v[32:33], v[32:33], v[40:41] op_sel_hi:[1,0]
	v_pk_mul_f32 v[22:23], v[22:23], v[40:41] op_sel_hi:[1,0]
	v_pk_mul_f32 v[24:25], v[24:25], v[40:41] op_sel_hi:[1,0]
	v_pk_mul_f32 v[26:27], v[26:27], v[40:41] op_sel_hi:[1,0]
	v_pk_mul_f32 v[28:29], v[28:29], v[40:41] op_sel_hi:[1,0]
	v_pk_mul_f32 v[18:19], v[18:19], v[40:41] op_sel_hi:[1,0]
	v_pk_mul_f32 v[20:21], v[20:21], v[40:41] op_sel_hi:[1,0]
	v_mul_f32_e32 v37, 0xbfb8aa3b, v30
	v_mul_f32_e32 v40, 0xbfb8aa3b, v31
	v_mul_f32_e32 v41, 0xbfb8aa3b, v32
	v_mul_f32_e32 v42, 0xbfb8aa3b, v33
	v_mul_f32_e32 v43, 0xbfb8aa3b, v22
	v_mul_f32_e32 v44, 0xbfb8aa3b, v23
	v_mul_f32_e32 v45, 0xbfb8aa3b, v24
	v_mul_f32_e32 v46, 0xbfb8aa3b, v25
	v_exp_f32_e32 v37, v37
	v_exp_f32_e32 v40, v40
	v_exp_f32_e32 v41, v41
	v_exp_f32_e32 v42, v42
	v_exp_f32_e32 v43, v43
	v_exp_f32_e32 v44, v44
	v_exp_f32_e32 v45, v45
	v_exp_f32_e32 v46, v46
	v_add_f32_e32 v37, 1.0, v37
	v_add_f32_e32 v47, 1.0, v40
	v_add_f32_e32 v48, 1.0, v41
	v_add_f32_e32 v49, 1.0, v42
	v_add_f32_e32 v50, 1.0, v43
	v_add_f32_e32 v51, 1.0, v44
	v_add_f32_e32 v52, 1.0, v45
	v_add_f32_e32 v53, 1.0, v46
	v_rcp_f32_e32 v40, v37
	v_rcp_f32_e32 v41, v47
	v_rcp_f32_e32 v42, v48
	v_rcp_f32_e32 v43, v49
	v_rcp_f32_e32 v44, v50
	v_rcp_f32_e32 v45, v51
	v_rcp_f32_e32 v46, v52
	v_rcp_f32_e32 v47, v53
	v_pk_mul_f32 v[30:31], v[30:31], v[40:41]
	v_pk_mul_f32 v[32:33], v[32:33], v[42:43]
	v_pk_mul_f32 v[22:23], v[22:23], v[44:45]
	v_pk_mul_f32 v[24:25], v[24:25], v[46:47]
	v_pk_mul_f32 v[26:27], v[26:27], v[30:31]
	v_pk_mul_f32 v[28:29], v[28:29], v[32:33]
	v_pk_mul_f32 v[22:23], v[18:19], v[22:23]
	v_pk_mul_f32 v[24:25], v[20:21], v[24:25]
	v_cvt_pk_bf16_f32 v18, v26, v27
	v_cvt_pk_bf16_f32 v19, v28, v29
	v_cvt_pk_bf16_f32 v20, v22, v23
	v_cvt_pk_bf16_f32 v21, v24, v25
	global_store_dwordx4 v[34:35], v[18:21], off
	s_nop 0
	s_and_b64 vcc, exec, s[42:43]
	s_nop 0
	v_ffbh_u32_e32 v20, v189
	v_min_u32_e32 v20, 32, v20
	v_lshlrev_b64 v[18:19], v20, v[188:189]
	v_min_u32_e32 v18, 1, v18
	v_or_b32_e32 v18, v19, v18
	v_cvt_f32_u32_e32 v18, v18
	v_sub_u32_e32 v19, 32, v20
	v_ldexp_f32 v18, v18, v19
	v_mul_f32_e32 v18, 0x35800000, v18
	v_fmamk_f32 v18, v18, 0x3a800000, v196
	v_mul_f32_e32 v19, 0x4b800000, v18
	v_cmp_gt_f32_e64 s[2:3], s23, v18
	s_nop 1
	v_cndmask_b32_e64 v18, v18, v19, s[2:3]
	v_rsq_f32_e32 v20, v18
	v_mad_i64_i32 v[18:19], s[16:17], v36, s1, v[142:143]
	v_lshl_add_u64 v[18:19], v[18:19], 0, v[144:145]
	v_mul_f32_e32 v21, 0x45800000, v20
	v_cndmask_b32_e64 v20, v20, v21, s[2:3]
	v_pk_mul_f32 v[14:15], v[14:15], v[20:21] op_sel_hi:[1,0]
	v_pk_mul_f32 v[16:17], v[16:17], v[20:21] op_sel_hi:[1,0]
	v_pk_mul_f32 v[6:7], v[6:7], v[20:21] op_sel_hi:[1,0]
	v_pk_mul_f32 v[8:9], v[8:9], v[20:21] op_sel_hi:[1,0]
	v_pk_mul_f32 v[10:11], v[10:11], v[20:21] op_sel_hi:[1,0]
	v_pk_mul_f32 v[12:13], v[12:13], v[20:21] op_sel_hi:[1,0]
	v_pk_mul_f32 v[2:3], v[2:3], v[20:21] op_sel_hi:[1,0]
	v_pk_mul_f32 v[4:5], v[4:5], v[20:21] op_sel_hi:[1,0]
	v_mul_f32_e32 v20, 0xbfb8aa3b, v14
	v_mul_f32_e32 v21, 0xbfb8aa3b, v15
	v_mul_f32_e32 v22, 0xbfb8aa3b, v16
	v_mul_f32_e32 v23, 0xbfb8aa3b, v17
	v_mul_f32_e32 v24, 0xbfb8aa3b, v6
	v_mul_f32_e32 v25, 0xbfb8aa3b, v7
	v_mul_f32_e32 v26, 0xbfb8aa3b, v8
	v_mul_f32_e32 v27, 0xbfb8aa3b, v9
	v_exp_f32_e32 v20, v20
	v_exp_f32_e32 v21, v21
	v_exp_f32_e32 v22, v22
	v_exp_f32_e32 v23, v23
	v_exp_f32_e32 v24, v24
	v_exp_f32_e32 v25, v25
	v_exp_f32_e32 v26, v26
	v_exp_f32_e32 v27, v27
	v_add_f32_e32 v20, 1.0, v20
	v_add_f32_e32 v21, 1.0, v21
	v_add_f32_e32 v22, 1.0, v22
	v_add_f32_e32 v23, 1.0, v23
	v_add_f32_e32 v24, 1.0, v24
	v_add_f32_e32 v25, 1.0, v25
	v_add_f32_e32 v26, 1.0, v26
	v_add_f32_e32 v27, 1.0, v27
	v_rcp_f32_e32 v20, v20
	v_rcp_f32_e32 v21, v21
	v_rcp_f32_e32 v22, v22
	v_rcp_f32_e32 v23, v23
	v_rcp_f32_e32 v24, v24
	v_rcp_f32_e32 v25, v25
	v_rcp_f32_e32 v26, v26
	v_rcp_f32_e32 v27, v27
	v_pk_mul_f32 v[14:15], v[14:15], v[20:21]
	v_pk_mul_f32 v[16:17], v[16:17], v[22:23]
	v_pk_mul_f32 v[6:7], v[6:7], v[24:25]
	v_pk_mul_f32 v[8:9], v[8:9], v[26:27]
	v_pk_mul_f32 v[10:11], v[10:11], v[14:15]
	v_pk_mul_f32 v[12:13], v[12:13], v[16:17]
	v_pk_mul_f32 v[6:7], v[2:3], v[6:7]
	v_pk_mul_f32 v[8:9], v[4:5], v[8:9]
	v_cvt_pk_bf16_f32 v2, v10, v11
	v_cvt_pk_bf16_f32 v3, v12, v13
	v_cvt_pk_bf16_f32 v4, v6, v7
	v_cvt_pk_bf16_f32 v5, v8, v9
	s_mov_b64 s[2:3], -1
	global_store_dwordx4 v[18:19], v[2:5], off
	s_cbranch_vccnz .LBB0_490
	s_andn2_b64 vcc, exec, s[40:41]
	s_cbranch_vccnz .LBB0_489
	s_barrier
	s_branch .LBB0_489

; template <class Epi, class Sched, bool ALIGN_EPI = false, bool SP2 = false>
; __device__ __forceinline__ void gemm_phase(PG8_LAS unsigned char* lds, const Gemm g, const Sched& S, const Epi& E) {
;     ...
;     f32x4 acc[2][2][4][2];
; #pragma unroll
;     for (int a = 0; a < 2; ++a)
; #pragma unroll
;         for (int b = 0; b < 2; ++b)
; #pragma unroll
;             for (int m = 0; m < 4; ++m)
; #pragma unroll
;                 for (int n = 0; n < 2; ++n) acc[a][b][m][n] = (f32x4){0.f, 0.f, 0.f, 0.f};
;     bf16x8 At[4][2], B0[2][2], B1[2][2];
;     const char* cA = (const char*)g.A + (size_t)cur.pm * tstep; const char* cB = (const char*)g.Bt + (size_t)cur.pn * tstep;
.LBB0_1481:
	v_mov_b32_e32 v127, 0
	s_andn2_b64 vcc, exec, s[46:47]
	v_mov_b32_e32 v126, v127
	v_mov_b32_e32 v125, v127
	v_mov_b32_e32 v124, v127
	v_mov_b32_e32 v123, v127
	v_mov_b32_e32 v122, v127
	v_mov_b32_e32 v121, v127
	v_mov_b32_e32 v120, v127
	v_mov_b32_e32 v115, v127
	v_mov_b32_e32 v114, v127
	v_mov_b32_e32 v113, v127
	v_mov_b32_e32 v112, v127
	v_mov_b32_e32 v107, v127
	v_mov_b32_e32 v106, v127
	v_mov_b32_e32 v105, v127
	v_mov_b32_e32 v104, v127
	v_mov_b32_e32 v97, v127
	v_mov_b32_e32 v96, v127
	v_mov_b32_e32 v95, v127
	v_mov_b32_e32 v94, v127
	v_mov_b32_e32 v89, v127
	v_mov_b32_e32 v88, v127
	v_mov_b32_e32 v87, v127
	v_mov_b32_e32 v86, v127
	v_mov_b32_e32 v81, v127
	v_mov_b32_e32 v80, v127
	v_mov_b32_e32 v79, v127
	v_mov_b32_e32 v78, v127
	v_mov_b32_e32 v73, v127
	v_mov_b32_e32 v72, v127
	v_mov_b32_e32 v71, v127
	v_mov_b32_e32 v70, v127
	v_mov_b32_e32 v131, v127
	v_mov_b32_e32 v130, v127
	v_mov_b32_e32 v129, v127
	v_mov_b32_e32 v128, v127
	v_mov_b32_e32 v119, v127
	v_mov_b32_e32 v118, v127
	v_mov_b32_e32 v117, v127
	v_mov_b32_e32 v116, v127
	v_mov_b32_e32 v111, v127
	v_mov_b32_e32 v110, v127
	v_mov_b32_e32 v109, v127
	v_mov_b32_e32 v108, v127
	v_mov_b32_e32 v103, v127
	v_mov_b32_e32 v102, v127
	v_mov_b32_e32 v101, v127
	v_mov_b32_e32 v100, v127
	v_mov_b32_e32 v93, v127
	v_mov_b32_e32 v92, v127
	v_mov_b32_e32 v91, v127
	v_mov_b32_e32 v90, v127
	v_mov_b32_e32 v85, v127
	v_mov_b32_e32 v84, v127
	v_mov_b32_e32 v83, v127
	v_mov_b32_e32 v82, v127
	v_mov_b32_e32 v77, v127
	v_mov_b32_e32 v76, v127
	v_mov_b32_e32 v75, v127
	v_mov_b32_e32 v74, v127
	v_mov_b32_e32 v69, v127
	v_mov_b32_e32 v68, v127
	v_mov_b32_e32 v67, v127
	v_mov_b32_e32 v66, v127
	v_mov_b32_e32 v65, v127
	v_mov_b32_e32 v64, v127
	v_mov_b32_e32 v63, v127
	v_mov_b32_e32 v62, v127
	v_mov_b32_e32 v57, v127
	v_mov_b32_e32 v56, v127
	v_mov_b32_e32 v55, v127
	v_mov_b32_e32 v54, v127
	v_mov_b32_e32 v49, v127
	v_mov_b32_e32 v48, v127
	v_mov_b32_e32 v47, v127
	v_mov_b32_e32 v46, v127
	v_mov_b32_e32 v41, v127
	v_mov_b32_e32 v40, v127
	v_mov_b32_e32 v39, v127
	v_mov_b32_e32 v38, v127
	v_mov_b32_e32 v33, v127
	v_mov_b32_e32 v32, v127
	v_mov_b32_e32 v31, v127
	v_mov_b32_e32 v30, v127
	v_mov_b32_e32 v25, v127
	v_mov_b32_e32 v24, v127
	v_mov_b32_e32 v23, v127
	v_mov_b32_e32 v22, v127
	v_mov_b32_e32 v17, v127
	v_mov_b32_e32 v16, v127
	v_mov_b32_e32 v15, v127
	v_mov_b32_e32 v14, v127
	v_mov_b32_e32 v9, v127
	v_mov_b32_e32 v8, v127
	v_mov_b32_e32 v7, v127
	v_mov_b32_e32 v6, v127
	v_mov_b32_e32 v61, v127
	v_mov_b32_e32 v60, v127
	v_mov_b32_e32 v59, v127
	v_mov_b32_e32 v58, v127
	v_mov_b32_e32 v53, v127
	v_mov_b32_e32 v52, v127
	v_mov_b32_e32 v51, v127
	v_mov_b32_e32 v50, v127
	v_mov_b32_e32 v45, v127
	v_mov_b32_e32 v44, v127
	v_mov_b32_e32 v43, v127
	v_mov_b32_e32 v42, v127
	v_mov_b32_e32 v37, v127
	v_mov_b32_e32 v36, v127
	v_mov_b32_e32 v35, v127
	v_mov_b32_e32 v34, v127
	v_mov_b32_e32 v29, v127
	v_mov_b32_e32 v28, v127
	v_mov_b32_e32 v27, v127
	v_mov_b32_e32 v26, v127
	v_mov_b32_e32 v21, v127
	v_mov_b32_e32 v20, v127
	v_mov_b32_e32 v19, v127
	v_mov_b32_e32 v18, v127
	v_mov_b32_e32 v13, v127
	v_mov_b32_e32 v12, v127
	v_mov_b32_e32 v11, v127
	v_mov_b32_e32 v10, v127
	v_mov_b32_e32 v5, v127
	v_mov_b32_e32 v4, v127
	v_mov_b32_e32 v3, v127
	v_mov_b32_e32 v2, v127
	s_cbranch_vccnz .LBB0_1484
	s_add_u32 s2, s36, 0x80
	s_addc_u32 s3, s37, 0
	s_add_u32 s4, s34, 0x100
	v_mov_b32_e32 v2, 0
	s_addc_u32 s16, s35, 0
	s_mov_b32 s17, 0
	v_mov_b32_e32 v3, v2
	v_mov_b32_e32 v4, v2
	v_mov_b32_e32 v5, v2
	v_mov_b32_e32 v10, v2
	v_mov_b32_e32 v11, v2
	v_mov_b32_e32 v12, v2
	v_mov_b32_e32 v13, v2
	v_mov_b32_e32 v18, v2
	v_mov_b32_e32 v19, v2
	v_mov_b32_e32 v20, v2
	v_mov_b32_e32 v21, v2
	v_mov_b32_e32 v26, v2
	v_mov_b32_e32 v27, v2
	v_mov_b32_e32 v28, v2
	v_mov_b32_e32 v29, v2
	v_mov_b32_e32 v34, v2
	v_mov_b32_e32 v35, v2
	v_mov_b32_e32 v36, v2
	v_mov_b32_e32 v37, v2
	v_mov_b32_e32 v42, v2
	v_mov_b32_e32 v43, v2
	v_mov_b32_e32 v44, v2
	v_mov_b32_e32 v45, v2
	v_mov_b32_e32 v50, v2
	v_mov_b32_e32 v51, v2
	v_mov_b32_e32 v52, v2
	v_mov_b32_e32 v53, v2
	v_mov_b32_e32 v58, v2
	v_mov_b32_e32 v59, v2
	v_mov_b32_e32 v60, v2
	v_mov_b32_e32 v61, v2
	v_mov_b32_e32 v6, v2
	v_mov_b32_e32 v7, v2
	v_mov_b32_e32 v8, v2
	v_mov_b32_e32 v9, v2
	v_mov_b32_e32 v14, v2
	v_mov_b32_e32 v15, v2
	v_mov_b32_e32 v16, v2
	v_mov_b32_e32 v17, v2
	v_mov_b32_e32 v22, v2
	v_mov_b32_e32 v23, v2
	v_mov_b32_e32 v24, v2
	v_mov_b32_e32 v25, v2
	v_mov_b32_e32 v30, v2
	v_mov_b32_e32 v31, v2
	v_mov_b32_e32 v32, v2
	v_mov_b32_e32 v33, v2
	v_mov_b32_e32 v38, v2
	v_mov_b32_e32 v39, v2
	v_mov_b32_e32 v40, v2
	v_mov_b32_e32 v41, v2
	v_mov_b32_e32 v46, v2
	v_mov_b32_e32 v47, v2
	v_mov_b32_e32 v48, v2
	v_mov_b32_e32 v49, v2
	v_mov_b32_e32 v54, v2
	v_mov_b32_e32 v55, v2
	v_mov_b32_e32 v56, v2
	v_mov_b32_e32 v57, v2
	v_mov_b32_e32 v62, v2
	v_mov_b32_e32 v63, v2
	v_mov_b32_e32 v64, v2
	v_mov_b32_e32 v65, v2
	v_mov_b32_e32 v66, v2
	v_mov_b32_e32 v67, v2
	v_mov_b32_e32 v68, v2
	v_mov_b32_e32 v69, v2
	v_mov_b32_e32 v74, v2
	v_mov_b32_e32 v75, v2
	v_mov_b32_e32 v76, v2
	v_mov_b32_e32 v77, v2
	v_mov_b32_e32 v82, v2
	v_mov_b32_e32 v83, v2
	v_mov_b32_e32 v84, v2
	v_mov_b32_e32 v85, v2
	v_mov_b32_e32 v90, v2
	v_mov_b32_e32 v91, v2
	v_mov_b32_e32 v92, v2
	v_mov_b32_e32 v93, v2
	v_mov_b32_e32 v100, v2
	v_mov_b32_e32 v101, v2
	v_mov_b32_e32 v102, v2
	v_mov_b32_e32 v103, v2
	v_mov_b32_e32 v108, v2
	v_mov_b32_e32 v109, v2
	v_mov_b32_e32 v110, v2
	v_mov_b32_e32 v111, v2
	v_mov_b32_e32 v116, v2
	v_mov_b32_e32 v117, v2
	v_mov_b32_e32 v118, v2
	v_mov_b32_e32 v119, v2
	v_mov_b32_e32 v128, v2
	v_mov_b32_e32 v129, v2
	v_mov_b32_e32 v130, v2
	v_mov_b32_e32 v131, v2
	v_mov_b32_e32 v70, v2
	v_mov_b32_e32 v71, v2
	v_mov_b32_e32 v72, v2
	v_mov_b32_e32 v73, v2
	v_mov_b32_e32 v78, v2
	v_mov_b32_e32 v79, v2
	v_mov_b32_e32 v80, v2
	v_mov_b32_e32 v81, v2
	v_mov_b32_e32 v86, v2
	v_mov_b32_e32 v87, v2
	v_mov_b32_e32 v88, v2
	v_mov_b32_e32 v89, v2
	v_mov_b32_e32 v94, v2
	v_mov_b32_e32 v95, v2
	v_mov_b32_e32 v96, v2
	v_mov_b32_e32 v97, v2
	v_mov_b32_e32 v104, v2
	v_mov_b32_e32 v105, v2
	v_mov_b32_e32 v106, v2
	v_mov_b32_e32 v107, v2
	v_mov_b32_e32 v112, v2
	v_mov_b32_e32 v113, v2
	v_mov_b32_e32 v114, v2
	v_mov_b32_e32 v115, v2
	v_mov_b32_e32 v120, v2
	v_mov_b32_e32 v121, v2
	v_mov_b32_e32 v122, v2
	v_mov_b32_e32 v123, v2
	v_mov_b32_e32 v124, v2
	v_mov_b32_e32 v125, v2
	v_mov_b32_e32 v126, v2
	v_mov_b32_e32 v127, v2
; #define PG8_STAGE(bufoff, gbase, voff) do { _Pragma("unroll") for (int _i = 0; _i < 2; ++_i) \
;         __builtin_amdgcn_global_load_lds((const unsigned*)((const char*)(gbase) + (voff)[_i]), (PG8_LAS unsigned*)(lds + (bufoff) + ldsw + _i * 8192), 16, 0, 0); } while (0)
; #define PG8_LDA(dst, b, h) do { _Pragma("unroll") for (int m = 0; m < 4; ++m) _Pragma("unroll") for (int k = 0; k < 2; ++k) dst[m][k] = *(const PG8_LAS bf16x8*)(lds + PG8_SA(b, h) + aoff + m * 2048 + k * 1024); } while (0)
; #define PG8_LDB(dst, b, h) do { _Pragma("unroll") for (int n = 0; n < 2; ++n) _Pragma("unroll") for (int k = 0; k < 2; ++k) dst[n][k] = *(const PG8_LAS bf16x8*)(lds + PG8_SB(b, h) + boff + n * 2048 + k * 1024); } while (0)
; #define PG8_MMA(ai, bj, At, Bt) do { __builtin_amdgcn_s_setprio(1); _Pragma("unroll") for (int m = 0; m < 4; ++m) _Pragma("unroll") for (int n = 0; n < 2; ++n) _Pragma("unroll") for (int k = 0; k < 2; ++k) \
;         acc[ai][bj][m][n] = __builtin_amdgcn_mfma_f32_16x16x32_bf16(Bt[n][k], At[m][k], acc[ai][bj][m][n], 0, 0, 0); __builtin_amdgcn_s_setprio(0); } while (0)
; #define PG8_WAIT_V(n) asm volatile("s_waitcnt vmcnt(" #n ")" ::: "memory")
; #define PG8_WAIT_L(n) asm volatile("s_waitcnt lgkmcnt(" #n ")" ::: "memory")
; #define PG8_BAR __builtin_amdgcn_s_barrier()
; #define PG8_SCHED __builtin_amdgcn_sched_barrier(0)
; template <class Epi, class Sched, bool ALIGN_EPI = false, bool SP2 = false>
; __device__ __forceinline__ void gemm_phase(PG8_LAS unsigned char* lds, const Gemm g, const Sched& S, const Epi& E) {
;     ...
;             PG8_LDB(B0, 0, 0); PG8_LDB(B1, 0, 1); PG8_SCHED; PG8_LDA(At, 0, 0); PG8_STAGE(PG8_SA(1, 1), a1 + hstep, voffA);
;             PG8_WAIT_V(8); PG8_WAIT_L(0); PG8_BAR; PG8_MMA(0, 0, At, B0); PG8_MMA(0, 1, At, B1); PG8_BAR; PG8_SCHED;
;             PG8_LDA(At, 0, 1); PG8_STAGE(PG8_SB(0, 0), b2, voffB); PG8_STAGE(PG8_SB(0, 1), b2 + hstep, voffB); PG8_STAGE(PG8_SA(0, 0), a2, voffA);
;             PG8_WAIT_V(8); PG8_WAIT_L(0); PG8_BAR; PG8_MMA(1, 0, At, B0); PG8_MMA(1, 1, At, B1); PG8_BAR; PG8_SCHED;
.LBB0_1483:
	s_add_i32 s22, s17, 2
	s_add_u32 s28, s2, 0x80
	s_addc_u32 s30, s3, 0
	s_add_i32 s33, 0, 0x10000
	s_cmp_eq_u32 s70, s17
	s_cselect_b32 s35, s51, s30
	s_cselect_b32 s34, s50, s28
	v_add_u32_e32 v146, s33, v148
	s_cselect_b32 s31, s53, s16
	s_cselect_b32 s30, s52, s4
	s_add_i32 s17, 0, 0x14000
	ds_read_b128 v[142:145], v146
	ds_read_b128 v[154:157], v146 offset:1024
	ds_read_b128 v[158:161], v146 offset:2048
	ds_read_b128 v[162:165], v146 offset:3072
	v_add_u32_e32 v146, s17, v148
	ds_read_b128 v[166:169], v146
	ds_read_b128 v[170:173], v146 offset:1024
	ds_read_b128 v[174:177], v146 offset:2048
	ds_read_b128 v[178:181], v146 offset:3072
	v_lshl_add_u64 v[146:147], s[2:3], 0, v[138:139]
	s_add_i32 m0, s64, 0xc000
	ds_read_b128 v[182:185], v153
	ds_read_b128 v[186:189], v153 offset:1024
	ds_read_b128 v[190:193], v153 offset:2048
	ds_read_b128 v[208:211], v153 offset:3072
	ds_read_b128 v[212:215], v153 offset:4096
	ds_read_b128 v[216:219], v153 offset:5120
	ds_read_b128 v[220:223], v153 offset:6144
	ds_read_b128 v[228:231], v153 offset:7168
	global_load_lds_dwordx4 v[146:147], off
	v_lshl_add_u64 v[146:147], s[2:3], 0, v[140:141]
	s_add_i32 m0, s64, 0xe000
	s_nop 0
	global_load_lds_dwordx4 v[146:147], off
	s_waitcnt vmcnt(8)
	s_waitcnt lgkmcnt(0)
	s_barrier
	s_setprio 1
	s_waitcnt lgkmcnt(0)
	v_mfma_f32_16x16x32_bf16 v[124:127], v[142:145], v[182:185], v[124:127]
	v_mfma_f32_16x16x32_bf16 v[120:123], v[158:161], v[182:185], v[120:123]
	v_mfma_f32_16x16x32_bf16 v[112:115], v[142:145], v[190:193], v[112:115]
	v_mfma_f32_16x16x32_bf16 v[104:107], v[158:161], v[190:193], v[104:107]
	v_mfma_f32_16x16x32_bf16 v[94:97], v[142:145], v[212:215], v[94:97]
	v_mfma_f32_16x16x32_bf16 v[86:89], v[158:161], v[212:215], v[86:89]
	v_mfma_f32_16x16x32_bf16 v[78:81], v[142:145], v[220:223], v[78:81]
	v_mfma_f32_16x16x32_bf16 v[70:73], v[158:161], v[220:223], v[70:73]
	v_mfma_f32_16x16x32_bf16 v[124:127], v[154:157], v[186:189], v[124:127]
	v_mfma_f32_16x16x32_bf16 v[120:123], v[162:165], v[186:189], v[120:123]
	v_mfma_f32_16x16x32_bf16 v[112:115], v[154:157], v[208:211], v[112:115]
	v_mfma_f32_16x16x32_bf16 v[104:107], v[162:165], v[208:211], v[104:107]
	v_mfma_f32_16x16x32_bf16 v[94:97], v[154:157], v[216:219], v[94:97]
	v_mfma_f32_16x16x32_bf16 v[86:89], v[162:165], v[216:219], v[86:89]
	v_mfma_f32_16x16x32_bf16 v[78:81], v[154:157], v[228:231], v[78:81]
	v_mfma_f32_16x16x32_bf16 v[70:73], v[162:165], v[228:231], v[70:73]
	s_setprio 0
	s_setprio 1
	v_mfma_f32_16x16x32_bf16 v[128:131], v[166:169], v[182:185], v[128:131]
	v_mfma_f32_16x16x32_bf16 v[116:119], v[174:177], v[182:185], v[116:119]
	v_mfma_f32_16x16x32_bf16 v[108:111], v[166:169], v[190:193], v[108:111]
	v_mfma_f32_16x16x32_bf16 v[100:103], v[174:177], v[190:193], v[100:103]
	v_mfma_f32_16x16x32_bf16 v[90:93], v[166:169], v[212:215], v[90:93]
	v_mfma_f32_16x16x32_bf16 v[82:85], v[174:177], v[212:215], v[82:85]
	v_mfma_f32_16x16x32_bf16 v[74:77], v[166:169], v[220:223], v[74:77]
	v_mfma_f32_16x16x32_bf16 v[66:69], v[174:177], v[220:223], v[66:69]
	v_mfma_f32_16x16x32_bf16 v[128:131], v[170:173], v[186:189], v[128:131]
	v_mfma_f32_16x16x32_bf16 v[116:119], v[178:181], v[186:189], v[116:119]
	v_mfma_f32_16x16x32_bf16 v[108:111], v[170:173], v[208:211], v[108:111]
	v_mfma_f32_16x16x32_bf16 v[100:103], v[178:181], v[208:211], v[100:103]
	v_mfma_f32_16x16x32_bf16 v[90:93], v[170:173], v[216:219], v[90:93]
	v_mfma_f32_16x16x32_bf16 v[82:85], v[178:181], v[216:219], v[82:85]
	v_mfma_f32_16x16x32_bf16 v[74:77], v[170:173], v[228:231], v[74:77]
	v_mfma_f32_16x16x32_bf16 v[66:69], v[178:181], v[228:231], v[66:69]
	s_setprio 0
	s_barrier
	s_add_i32 s28, s33, s57
	v_lshl_add_u64 v[146:147], s[30:31], 0, v[98:99]
	s_mov_b32 m0, s28
	ds_read_b128 v[182:185], v153 offset:16384
	ds_read_b128 v[186:189], v153 offset:17408
	ds_read_b128 v[190:193], v153 offset:18432
	ds_read_b128 v[208:211], v153 offset:19456
	ds_read_b128 v[212:215], v153 offset:20480
	ds_read_b128 v[216:219], v153 offset:21504
	ds_read_b128 v[220:223], v153 offset:22528
	ds_read_b128 v[228:231], v153 offset:23552
	global_load_lds_dwordx4 v[146:147], off
	s_add_i32 m0, s28, 0x2000
	v_lshl_add_u64 v[224:225], s[30:31], 0, v[132:133]
	s_add_u32 s30, s30, s8
	s_addc_u32 s31, s31, s9
	s_add_i32 s17, s17, s57
	global_load_lds_dwordx4 v[224:225], off
	v_lshl_add_u64 v[232:233], s[30:31], 0, v[98:99]
	s_mov_b32 m0, s17
	v_lshl_add_u64 v[234:235], s[30:31], 0, v[132:133]
	global_load_lds_dwordx4 v[232:233], off
	s_add_i32 m0, s17, 0x2000
	v_lshl_add_u64 v[236:237], s[34:35], 0, v[136:137]
	global_load_lds_dwordx4 v[234:235], off
	s_mov_b32 m0, s64
	v_lshl_add_u64 v[238:239], s[34:35], 0, v[134:135]
	global_load_lds_dwordx4 v[236:237], off
	s_mov_b32 m0, s65
	s_nop 0
	global_load_lds_dwordx4 v[238:239], off
	s_waitcnt vmcnt(8)
	s_waitcnt lgkmcnt(0)
	s_barrier
; #define PG8_STAGE(bufoff, gbase, voff) do { _Pragma("unroll") for (int _i = 0; _i < 2; ++_i) \
;         __builtin_amdgcn_global_load_lds((const unsigned*)((const char*)(gbase) + (voff)[_i]), (PG8_LAS unsigned*)(lds + (bufoff) + ldsw + _i * 8192), 16, 0, 0); } while (0)
; #define PG8_LDA(dst, b, h) do { _Pragma("unroll") for (int m = 0; m < 4; ++m) _Pragma("unroll") for (int k = 0; k < 2; ++k) dst[m][k] = *(const PG8_LAS bf16x8*)(lds + PG8_SA(b, h) + aoff + m * 2048 + k * 1024); } while (0)
; #define PG8_LDB(dst, b, h) do { _Pragma("unroll") for (int n = 0; n < 2; ++n) _Pragma("unroll") for (int k = 0; k < 2; ++k) dst[n][k] = *(const PG8_LAS bf16x8*)(lds + PG8_SB(b, h) + boff + n * 2048 + k * 1024); } while (0)
; #define PG8_MMA(ai, bj, At, Bt) do { __builtin_amdgcn_s_setprio(1); _Pragma("unroll") for (int m = 0; m < 4; ++m) _Pragma("unroll") for (int n = 0; n < 2; ++n) _Pragma("unroll") for (int k = 0; k < 2; ++k) \
;         acc[ai][bj][m][n] = __builtin_amdgcn_mfma_f32_16x16x32_bf16(Bt[n][k], At[m][k], acc[ai][bj][m][n], 0, 0, 0); __builtin_amdgcn_s_setprio(0); } while (0)
; #define PG8_WAIT_V(n) asm volatile("s_waitcnt vmcnt(" #n ")" ::: "memory")
; #define PG8_WAIT_L(n) asm volatile("s_waitcnt lgkmcnt(" #n ")" ::: "memory")
; #define PG8_BAR __builtin_amdgcn_s_barrier()
; #define PG8_SCHED __builtin_amdgcn_sched_barrier(0)
; template <class Epi, class Sched, bool ALIGN_EPI = false, bool SP2 = false>
; __device__ __forceinline__ void gemm_phase(PG8_LAS unsigned char* lds, const Gemm g, const Sched& S, const Epi& E) {
;     ...
;             PG8_WAIT_V(8); PG8_WAIT_L(0); PG8_BAR; PG8_MMA(1, 0, At, B0); PG8_MMA(1, 1, At, B1); PG8_BAR; PG8_SCHED;
;             PG8_LDB(B0, 1, 0); PG8_LDB(B1, 1, 1); PG8_SCHED; PG8_LDA(At, 1, 0); PG8_STAGE(PG8_SA(0, 1), a2 + hstep, voffA);
;             PG8_WAIT_V(8); PG8_WAIT_L(0); PG8_BAR; PG8_MMA(0, 0, At, B0); PG8_MMA(0, 1, At, B1); PG8_BAR; PG8_SCHED;
	s_setprio 1
	s_waitcnt lgkmcnt(0)
	v_mfma_f32_16x16x32_bf16 v[62:65], v[142:145], v[182:185], v[62:65]
	v_mfma_f32_16x16x32_bf16 v[54:57], v[158:161], v[182:185], v[54:57]
	v_mfma_f32_16x16x32_bf16 v[46:49], v[142:145], v[190:193], v[46:49]
	v_mfma_f32_16x16x32_bf16 v[38:41], v[158:161], v[190:193], v[38:41]
	v_mfma_f32_16x16x32_bf16 v[30:33], v[142:145], v[212:215], v[30:33]
	v_mfma_f32_16x16x32_bf16 v[22:25], v[158:161], v[212:215], v[22:25]
	v_mfma_f32_16x16x32_bf16 v[14:17], v[142:145], v[220:223], v[14:17]
	v_mfma_f32_16x16x32_bf16 v[6:9], v[158:161], v[220:223], v[6:9]
	v_mfma_f32_16x16x32_bf16 v[62:65], v[154:157], v[186:189], v[62:65]
	v_mfma_f32_16x16x32_bf16 v[54:57], v[162:165], v[186:189], v[54:57]
	v_mfma_f32_16x16x32_bf16 v[46:49], v[154:157], v[208:211], v[46:49]
	v_mfma_f32_16x16x32_bf16 v[38:41], v[162:165], v[208:211], v[38:41]
	v_mfma_f32_16x16x32_bf16 v[30:33], v[154:157], v[216:219], v[30:33]
	v_mfma_f32_16x16x32_bf16 v[22:25], v[162:165], v[216:219], v[22:25]
	v_mfma_f32_16x16x32_bf16 v[14:17], v[154:157], v[228:231], v[14:17]
	v_mfma_f32_16x16x32_bf16 v[6:9], v[162:165], v[228:231], v[6:9]
	s_setprio 0
	s_setprio 1
	v_mfma_f32_16x16x32_bf16 v[58:61], v[166:169], v[182:185], v[58:61]
	v_mfma_f32_16x16x32_bf16 v[50:53], v[174:177], v[182:185], v[50:53]
	v_mfma_f32_16x16x32_bf16 v[42:45], v[166:169], v[190:193], v[42:45]
	v_mfma_f32_16x16x32_bf16 v[34:37], v[174:177], v[190:193], v[34:37]
	v_mfma_f32_16x16x32_bf16 v[26:29], v[166:169], v[212:215], v[26:29]
	v_mfma_f32_16x16x32_bf16 v[18:21], v[174:177], v[212:215], v[18:21]
	v_mfma_f32_16x16x32_bf16 v[10:13], v[166:169], v[220:223], v[10:13]
	v_mfma_f32_16x16x32_bf16 v[2:5], v[174:177], v[220:223], v[2:5]
	v_mfma_f32_16x16x32_bf16 v[58:61], v[170:173], v[186:189], v[58:61]
	v_mfma_f32_16x16x32_bf16 v[50:53], v[178:181], v[186:189], v[50:53]
	v_mfma_f32_16x16x32_bf16 v[42:45], v[170:173], v[208:211], v[42:45]
	v_mfma_f32_16x16x32_bf16 v[34:37], v[178:181], v[208:211], v[34:37]
	v_mfma_f32_16x16x32_bf16 v[26:29], v[170:173], v[216:219], v[26:29]
	v_mfma_f32_16x16x32_bf16 v[18:21], v[178:181], v[216:219], v[18:21]
	v_mfma_f32_16x16x32_bf16 v[10:13], v[170:173], v[228:231], v[10:13]
	v_mfma_f32_16x16x32_bf16 v[2:5], v[178:181], v[228:231], v[2:5]
	s_setprio 0
	s_barrier
	s_add_i32 s17, 0, 0x18000
	s_add_i32 s28, 0, 0x1c000
	v_add_u32_e32 v162, s17, v148
	v_add_u32_e32 v178, s28, v148
	ds_read_b128 v[142:145], v162
	ds_read_b128 v[154:157], v162 offset:1024
	ds_read_b128 v[158:161], v162 offset:2048
	ds_read_b128 v[162:165], v162 offset:3072
	ds_read_b128 v[166:169], v178
	ds_read_b128 v[170:173], v178 offset:1024
	ds_read_b128 v[174:177], v178 offset:2048
	ds_read_b128 v[178:181], v178 offset:3072
	s_add_u32 s30, s34, s8
	s_addc_u32 s31, s35, s9
	s_mov_b32 m0, s66
	v_lshl_add_u64 v[240:241], s[30:31], 0, v[136:137]
	ds_read_b128 v[182:185], v153 offset:32768
	ds_read_b128 v[186:189], v153 offset:33792
	ds_read_b128 v[190:193], v153 offset:34816
	ds_read_b128 v[208:211], v153 offset:35840
	ds_read_b128 v[212:215], v153 offset:36864
	ds_read_b128 v[216:219], v153 offset:37888
	ds_read_b128 v[220:223], v153 offset:38912
	ds_read_b128 v[228:231], v153 offset:39936
	global_load_lds_dwordx4 v[240:241], off
	v_lshl_add_u64 v[240:241], s[30:31], 0, v[134:135]
	s_mov_b32 m0, s67
	s_nop 0
	global_load_lds_dwordx4 v[240:241], off
	s_waitcnt vmcnt(8)
	s_waitcnt lgkmcnt(0)
	s_barrier
	s_setprio 1
	s_waitcnt lgkmcnt(0)
	v_mfma_f32_16x16x32_bf16 v[124:127], v[142:145], v[182:185], v[124:127]
	v_mfma_f32_16x16x32_bf16 v[120:123], v[158:161], v[182:185], v[120:123]
	v_mfma_f32_16x16x32_bf16 v[112:115], v[142:145], v[190:193], v[112:115]
	v_mfma_f32_16x16x32_bf16 v[104:107], v[158:161], v[190:193], v[104:107]
	v_mfma_f32_16x16x32_bf16 v[94:97], v[142:145], v[212:215], v[94:97]
	v_mfma_f32_16x16x32_bf16 v[86:89], v[158:161], v[212:215], v[86:89]
	v_mfma_f32_16x16x32_bf16 v[78:81], v[142:145], v[220:223], v[78:81]
	v_mfma_f32_16x16x32_bf16 v[70:73], v[158:161], v[220:223], v[70:73]
	v_mfma_f32_16x16x32_bf16 v[124:127], v[154:157], v[186:189], v[124:127]
	v_mfma_f32_16x16x32_bf16 v[120:123], v[162:165], v[186:189], v[120:123]
	v_mfma_f32_16x16x32_bf16 v[112:115], v[154:157], v[208:211], v[112:115]
	v_mfma_f32_16x16x32_bf16 v[104:107], v[162:165], v[208:211], v[104:107]
	v_mfma_f32_16x16x32_bf16 v[94:97], v[154:157], v[216:219], v[94:97]
	v_mfma_f32_16x16x32_bf16 v[86:89], v[162:165], v[216:219], v[86:89]
	v_mfma_f32_16x16x32_bf16 v[78:81], v[154:157], v[228:231], v[78:81]
	v_mfma_f32_16x16x32_bf16 v[70:73], v[162:165], v[228:231], v[70:73]
	s_setprio 0
	s_setprio 1
	v_mfma_f32_16x16x32_bf16 v[128:131], v[166:169], v[182:185], v[128:131]
	v_mfma_f32_16x16x32_bf16 v[116:119], v[174:177], v[182:185], v[116:119]
	v_mfma_f32_16x16x32_bf16 v[108:111], v[166:169], v[190:193], v[108:111]
	v_mfma_f32_16x16x32_bf16 v[100:103], v[174:177], v[190:193], v[100:103]
	v_mfma_f32_16x16x32_bf16 v[90:93], v[166:169], v[212:215], v[90:93]
	v_mfma_f32_16x16x32_bf16 v[82:85], v[174:177], v[212:215], v[82:85]
	v_mfma_f32_16x16x32_bf16 v[74:77], v[166:169], v[220:223], v[74:77]
	v_mfma_f32_16x16x32_bf16 v[66:69], v[174:177], v[220:223], v[66:69]
	v_mfma_f32_16x16x32_bf16 v[128:131], v[170:173], v[186:189], v[128:131]
	v_mfma_f32_16x16x32_bf16 v[116:119], v[178:181], v[186:189], v[116:119]
	v_mfma_f32_16x16x32_bf16 v[108:111], v[170:173], v[208:211], v[108:111]
	v_mfma_f32_16x16x32_bf16 v[100:103], v[178:181], v[208:211], v[100:103]
	v_mfma_f32_16x16x32_bf16 v[90:93], v[170:173], v[216:219], v[90:93]
	v_mfma_f32_16x16x32_bf16 v[82:85], v[178:181], v[216:219], v[82:85]
	v_mfma_f32_16x16x32_bf16 v[74:77], v[170:173], v[228:231], v[74:77]
	v_mfma_f32_16x16x32_bf16 v[66:69], v[178:181], v[228:231], v[66:69]
	s_setprio 0
	s_barrier
; #define PG8_STAGE(bufoff, gbase, voff) do { _Pragma("unroll") for (int _i = 0; _i < 2; ++_i) \
;         __builtin_amdgcn_global_load_lds((const unsigned*)((const char*)(gbase) + (voff)[_i]), (PG8_LAS unsigned*)(lds + (bufoff) + ldsw + _i * 8192), 16, 0, 0); } while (0)
; #define PG8_LDA(dst, b, h) do { _Pragma("unroll") for (int m = 0; m < 4; ++m) _Pragma("unroll") for (int k = 0; k < 2; ++k) dst[m][k] = *(const PG8_LAS bf16x8*)(lds + PG8_SA(b, h) + aoff + m * 2048 + k * 1024); } while (0)
; #define PG8_MMA(ai, bj, At, Bt) do { __builtin_amdgcn_s_setprio(1); _Pragma("unroll") for (int m = 0; m < 4; ++m) _Pragma("unroll") for (int n = 0; n < 2; ++n) _Pragma("unroll") for (int k = 0; k < 2; ++k) \
;         acc[ai][bj][m][n] = __builtin_amdgcn_mfma_f32_16x16x32_bf16(Bt[n][k], At[m][k], acc[ai][bj][m][n], 0, 0, 0); __builtin_amdgcn_s_setprio(0); } while (0)
; #define PG8_WAIT_V(n) asm volatile("s_waitcnt vmcnt(" #n ")" ::: "memory")
; #define PG8_WAIT_L(n) asm volatile("s_waitcnt lgkmcnt(" #n ")" ::: "memory")
; #define PG8_BAR __builtin_amdgcn_s_barrier()
; #define PG8_SCHED __builtin_amdgcn_sched_barrier(0)
; template <class Epi, class Sched, bool ALIGN_EPI = false, bool SP2 = false>
; __device__ __forceinline__ void gemm_phase(PG8_LAS unsigned char* lds, const Gemm g, const Sched& S, const Epi& E) {
;     ...
;             PG8_LDA(At, 1, 1); PG8_STAGE(PG8_SB(1, 0), b3, voffB); PG8_STAGE(PG8_SB(1, 1), b3 + hstep, voffB); PG8_STAGE(PG8_SA(1, 0), a3, voffA);
;             PG8_WAIT_V(8); PG8_WAIT_L(0); PG8_BAR; PG8_MMA(1, 0, At, B0); PG8_MMA(1, 1, At, B1); PG8_BAR; PG8_SCHED;
	s_add_i32 s17, s17, s57
	v_lshl_add_u64 v[146:147], v[146:147], 0, s[24:25]
	s_mov_b32 m0, s17
	ds_read_b128 v[182:185], v153 offset:49152
	ds_read_b128 v[186:189], v153 offset:50176
	ds_read_b128 v[190:193], v153 offset:51200
	ds_read_b128 v[208:211], v153 offset:52224
	ds_read_b128 v[212:215], v153 offset:53248
	ds_read_b128 v[216:219], v153 offset:54272
	ds_read_b128 v[220:223], v153 offset:55296
	ds_read_b128 v[228:231], v153 offset:56320
	global_load_lds_dwordx4 v[146:147], off
	v_lshl_add_u64 v[146:147], v[224:225], 0, s[24:25]
	s_add_i32 m0, s17, 0x2000
	s_add_i32 s17, s28, s57
	global_load_lds_dwordx4 v[146:147], off
	v_lshl_add_u64 v[146:147], v[232:233], 0, s[24:25]
	s_mov_b32 m0, s17
	s_nop 0
	global_load_lds_dwordx4 v[146:147], off
	v_lshl_add_u64 v[146:147], v[234:235], 0, s[24:25]
	s_add_i32 m0, s17, 0x2000
	s_nop 0
	global_load_lds_dwordx4 v[146:147], off
	v_lshl_add_u64 v[146:147], v[236:237], 0, s[24:25]
	s_mov_b32 m0, s68
	s_nop 0
	global_load_lds_dwordx4 v[146:147], off
	v_lshl_add_u64 v[146:147], v[238:239], 0, s[24:25]
	s_mov_b32 m0, s69
	s_nop 0
	global_load_lds_dwordx4 v[146:147], off
	s_waitcnt vmcnt(8)
	s_waitcnt lgkmcnt(0)
	s_barrier
	s_setprio 1
	s_waitcnt lgkmcnt(0)
	v_mfma_f32_16x16x32_bf16 v[62:65], v[142:145], v[182:185], v[62:65]
	v_mfma_f32_16x16x32_bf16 v[54:57], v[158:161], v[182:185], v[54:57]
	v_mfma_f32_16x16x32_bf16 v[46:49], v[142:145], v[190:193], v[46:49]
	v_mfma_f32_16x16x32_bf16 v[38:41], v[158:161], v[190:193], v[38:41]
	v_mfma_f32_16x16x32_bf16 v[30:33], v[142:145], v[212:215], v[30:33]
	v_mfma_f32_16x16x32_bf16 v[22:25], v[158:161], v[212:215], v[22:25]
	v_mfma_f32_16x16x32_bf16 v[14:17], v[142:145], v[220:223], v[14:17]
	v_mfma_f32_16x16x32_bf16 v[6:9], v[158:161], v[220:223], v[6:9]
	v_mfma_f32_16x16x32_bf16 v[62:65], v[154:157], v[186:189], v[62:65]
	v_mfma_f32_16x16x32_bf16 v[54:57], v[162:165], v[186:189], v[54:57]
	v_mfma_f32_16x16x32_bf16 v[46:49], v[154:157], v[208:211], v[46:49]
	v_mfma_f32_16x16x32_bf16 v[38:41], v[162:165], v[208:211], v[38:41]
	v_mfma_f32_16x16x32_bf16 v[30:33], v[154:157], v[216:219], v[30:33]
	v_mfma_f32_16x16x32_bf16 v[22:25], v[162:165], v[216:219], v[22:25]
	v_mfma_f32_16x16x32_bf16 v[14:17], v[154:157], v[228:231], v[14:17]
	v_mfma_f32_16x16x32_bf16 v[6:9], v[162:165], v[228:231], v[6:9]
	s_setprio 0
	s_setprio 1
	v_mfma_f32_16x16x32_bf16 v[58:61], v[166:169], v[182:185], v[58:61]
	v_mfma_f32_16x16x32_bf16 v[50:53], v[174:177], v[182:185], v[50:53]
	v_mfma_f32_16x16x32_bf16 v[42:45], v[166:169], v[190:193], v[42:45]
	v_mfma_f32_16x16x32_bf16 v[34:37], v[174:177], v[190:193], v[34:37]
	v_mfma_f32_16x16x32_bf16 v[26:29], v[166:169], v[212:215], v[26:29]
	v_mfma_f32_16x16x32_bf16 v[18:21], v[174:177], v[212:215], v[18:21]
	v_mfma_f32_16x16x32_bf16 v[10:13], v[166:169], v[220:223], v[10:13]
	v_mfma_f32_16x16x32_bf16 v[2:5], v[174:177], v[220:223], v[2:5]
	v_mfma_f32_16x16x32_bf16 v[58:61], v[170:173], v[186:189], v[58:61]
	v_mfma_f32_16x16x32_bf16 v[50:53], v[178:181], v[186:189], v[50:53]
	v_mfma_f32_16x16x32_bf16 v[42:45], v[170:173], v[208:211], v[42:45]
	v_mfma_f32_16x16x32_bf16 v[34:37], v[178:181], v[208:211], v[34:37]
	v_mfma_f32_16x16x32_bf16 v[26:29], v[170:173], v[216:219], v[26:29]
	v_mfma_f32_16x16x32_bf16 v[18:21], v[178:181], v[216:219], v[18:21]
	v_mfma_f32_16x16x32_bf16 v[10:13], v[170:173], v[228:231], v[10:13]
	v_mfma_f32_16x16x32_bf16 v[2:5], v[178:181], v[228:231], v[2:5]
	s_setprio 0
	s_barrier
	s_add_u32 s2, s2, 0x100
	s_addc_u32 s3, s3, 0
	s_add_u32 s4, s4, 0x100
	s_addc_u32 s16, s16, 0
	s_cmp_ge_i32 s22, s18
	s_mov_b32 s17, s22
	s_cbranch_scc0 .LBB0_1483

; __device__ __forceinline__ unsigned pk2(float lo, float hi) { f32x2 v = {lo, hi}; bf16x2_t b = __builtin_convertvector(v, bf16x2_t); return __builtin_bit_cast(unsigned, b); }
; __device__ __forceinline__ float ex2(float x) { return __builtin_amdgcn_exp2f(x); }
; __device__ __forceinline__ float rcpf_(float x) { return __builtin_amdgcn_rcpf(x); }
; __device__ __forceinline__ float ssf(const ssq_t* p) { return (float)(*p) * (1.0f / 1048576.0f); }
;     __device__ __forceinline__ void operator()(const f32x4 (&acc)[2][2][4][2], const pg8::Unit& u, int wr, int wc, int fr, int fq) const {
; #pragma unroll
;         for (int ai = 0; ai < 2; ++ai)
; #pragma unroll
;             for (int m = 0; m < 4; ++m) {
;                 const int row = u.pm * 256 + ai * 128 + wr * 64 + m * 16 + fr;
;                 const float r = rsqrtf(ssf(SSin + row) * (1.0f / D) + EPS);
;                 const int col = u.pn * 128 + wc * 32 + fq * 8;
;                 float v[8];
; #pragma unroll
;                 for (int n = 0; n < 2; ++n) {
;                     const f32x4 g = acc[ai][0][m][n] * r, up = acc[ai][1][m][n] * r;
; #pragma unroll
;                     for (int i = 0; i < 4; ++i) v[4 * n + i] = g[i] * rcpf_(1.0f + ex2(-g[i] * LOG2E)) * up[i];
;                 }
;                 u32x4 w; w.x = pk2(v[0], v[1]); w.y = pk2(v[2], v[3]); w.z = pk2(v[4], v[5]); w.w = pk2(v[6], v[7]);
;                 *(u32x4*)(O + (size_t)row * FF + col) = w;
;             }
.LBB0_1486:
	s_lshl_b32 s2, s75, 8
	v_add_u32_e32 v190, s2, v1
	v_add_u32_e32 v192, s2, v149
	v_add_u32_e32 v208, s2, v150
	v_add_u32_e32 v210, s2, v151
	v_add_u32_e32 v212, 0x80, v190
	v_add_u32_e32 v214, 0x90, v190
	v_add_u32_e32 v216, 0xa0, v190
	v_add_u32_e32 v218, 0xb0, v190
	v_ashrrev_i32_e32 v191, 31, v190
	v_ashrrev_i32_e32 v193, 31, v192
	v_ashrrev_i32_e32 v209, 31, v208
	v_ashrrev_i32_e32 v211, 31, v210
	v_ashrrev_i32_e32 v213, 31, v212
	v_ashrrev_i32_e32 v215, 31, v214
	v_ashrrev_i32_e32 v217, 31, v216
	v_ashrrev_i32_e32 v219, 31, v218
	v_lshl_add_u64 v[220:221], v[190:191], 3, s[44:45]
	v_lshl_add_u64 v[222:223], v[192:193], 3, s[44:45]
	v_lshl_add_u64 v[224:225], v[208:209], 3, s[44:45]
	v_lshl_add_u64 v[228:229], v[210:211], 3, s[44:45]
	v_lshl_add_u64 v[230:231], v[212:213], 3, s[44:45]
	v_lshl_add_u64 v[232:233], v[214:215], 3, s[44:45]
	v_lshl_add_u64 v[234:235], v[216:217], 3, s[44:45]
	v_lshl_add_u64 v[236:237], v[218:219], 3, s[44:45]
	global_load_dwordx2 v[174:175], v[220:221], off
	global_load_dwordx2 v[176:177], v[222:223], off
	global_load_dwordx2 v[178:179], v[224:225], off
	global_load_dwordx2 v[180:181], v[228:229], off
	global_load_dwordx2 v[182:183], v[230:231], off
	global_load_dwordx2 v[184:185], v[232:233], off
	global_load_dwordx2 v[186:187], v[234:235], off
	global_load_dwordx2 v[188:189], v[236:237], off
	s_waitcnt vmcnt(0)
	v_add_u32_e32 v146, s2, v1
	v_ashrrev_i32_e32 v147, 31, v146
	v_lshl_add_u64 v[142:143], v[146:147], 3, s[44:45]
	s_nop 0
	v_lshl_or_b32 v154, s74, 7, v152
	v_ashrrev_i32_e32 v155, 31, v154
	v_mov_b64_e32 v[142:143], s[40:41]
	v_add_u32_e32 v156, s2, v149
	s_movk_i32 s1, 0x1600
	v_mad_i64_i32 v[158:159], s[16:17], v146, s1, v[142:143]
	s_nop 0
	v_ffbh_u32_e32 v147, v175
	v_min_u32_e32 v147, 32, v147
	v_lshlrev_b64 v[144:145], v147, v[174:175]
	v_min_u32_e32 v144, 1, v144
	v_or_b32_e32 v144, v145, v144
	v_cvt_f32_u32_e32 v157, v144
	v_sub_u32_e32 v147, 32, v147
	v_lshlrev_b64 v[144:145], 1, v[154:155]
	v_ldexp_f32 v147, v157, v147
	v_mul_f32_e32 v147, 0x35800000, v147
	v_fmamk_f32 v147, v147, 0x3a800000, v196
	v_mul_f32_e32 v154, 0x4b800000, v147
	v_cmp_gt_f32_e32 vcc, s23, v147
	v_ashrrev_i32_e32 v157, 31, v156
	s_nop 0
	v_cndmask_b32_e32 v147, v147, v154, vcc
	v_rsq_f32_e32 v147, v147
	v_lshl_add_u64 v[154:155], v[158:159], 0, v[144:145]
	v_lshl_add_u64 v[158:159], v[156:157], 3, s[44:45]
	v_mul_f32_e32 v157, 0x45800000, v147
	v_cndmask_b32_e32 v160, v147, v157, vcc
	v_pk_mul_f32 v[124:125], v[124:125], v[160:161] op_sel_hi:[1,0]
	v_pk_mul_f32 v[126:127], v[126:127], v[160:161] op_sel_hi:[1,0]
	v_pk_mul_f32 v[120:121], v[120:121], v[160:161] op_sel_hi:[1,0]
	v_pk_mul_f32 v[122:123], v[122:123], v[160:161] op_sel_hi:[1,0]
	v_pk_mul_f32 v[128:129], v[128:129], v[160:161] op_sel_hi:[1,0]
	v_pk_mul_f32 v[130:131], v[130:131], v[160:161] op_sel_hi:[1,0]
	v_pk_mul_f32 v[116:117], v[116:117], v[160:161] op_sel_hi:[1,0]
	v_pk_mul_f32 v[118:119], v[118:119], v[160:161] op_sel_hi:[1,0]
	v_mul_f32_e32 v147, 0xbfb8aa3b, v124
	v_mul_f32_e32 v157, 0xbfb8aa3b, v125
	v_mul_f32_e32 v160, 0xbfb8aa3b, v126
	v_mul_f32_e32 v161, 0xbfb8aa3b, v127
	v_mul_f32_e32 v162, 0xbfb8aa3b, v120
	v_mul_f32_e32 v163, 0xbfb8aa3b, v121
	v_mul_f32_e32 v164, 0xbfb8aa3b, v122
	v_mul_f32_e32 v165, 0xbfb8aa3b, v123
	v_exp_f32_e32 v147, v147
	v_exp_f32_e32 v157, v157
	v_exp_f32_e32 v160, v160
	v_exp_f32_e32 v161, v161
	v_exp_f32_e32 v162, v162
	v_exp_f32_e32 v163, v163
	v_exp_f32_e32 v164, v164
	v_exp_f32_e32 v165, v165
	v_add_f32_e32 v147, 1.0, v147
	v_add_f32_e32 v157, 1.0, v157
	v_add_f32_e32 v166, 1.0, v160
	v_add_f32_e32 v167, 1.0, v161
	v_add_f32_e32 v168, 1.0, v162
	v_add_f32_e32 v169, 1.0, v163
	v_add_f32_e32 v170, 1.0, v164
	v_add_f32_e32 v171, 1.0, v165
	v_rcp_f32_e32 v160, v147
	v_rcp_f32_e32 v161, v157
	v_rcp_f32_e32 v162, v166
	v_rcp_f32_e32 v163, v167
	v_rcp_f32_e32 v164, v168
	v_rcp_f32_e32 v165, v169
	v_rcp_f32_e32 v166, v170
	v_rcp_f32_e32 v167, v171
	v_pk_mul_f32 v[124:125], v[124:125], v[160:161]
	v_pk_mul_f32 v[126:127], v[126:127], v[162:163]
	v_pk_mul_f32 v[120:121], v[120:121], v[164:165]
	v_pk_mul_f32 v[122:123], v[122:123], v[166:167]
	v_pk_mul_f32 v[124:125], v[128:129], v[124:125]
	v_pk_mul_f32 v[126:127], v[130:131], v[126:127]
	v_pk_mul_f32 v[120:121], v[116:117], v[120:121]
	v_pk_mul_f32 v[122:123], v[118:119], v[122:123]
	v_cvt_pk_bf16_f32 v116, v124, v125
	v_cvt_pk_bf16_f32 v117, v126, v127
	v_cvt_pk_bf16_f32 v118, v120, v121
	v_cvt_pk_bf16_f32 v119, v122, v123
	global_store_dwordx4 v[154:155], v[116:119], off
	s_nop 0
	s_nop 0
	v_add_u32_e32 v118, s2, v150
	s_nop 0
	v_ffbh_u32_e32 v119, v177
	v_min_u32_e32 v119, 32, v119
	v_lshlrev_b64 v[116:117], v119, v[176:177]
	v_min_u32_e32 v116, 1, v116
	v_or_b32_e32 v116, v117, v116
	v_cvt_f32_u32_e32 v120, v116
	v_sub_u32_e32 v119, 32, v119
	v_mad_i64_i32 v[116:117], s[16:17], v156, s1, v[142:143]
	v_ldexp_f32 v119, v120, v119
	v_mul_f32_e32 v119, 0x35800000, v119
	v_fmamk_f32 v119, v119, 0x3a800000, v196
	v_mul_f32_e32 v120, 0x4b800000, v119
	v_cmp_gt_f32_e32 vcc, s23, v119
	v_lshl_add_u64 v[116:117], v[116:117], 0, v[144:145]
	s_nop 0
	v_cndmask_b32_e32 v119, v119, v120, vcc
	v_rsq_f32_e32 v122, v119
	v_ashrrev_i32_e32 v119, 31, v118
	v_lshl_add_u64 v[120:121], v[118:119], 3, s[44:45]
	v_mul_f32_e32 v119, 0x45800000, v122
	v_cndmask_b32_e32 v122, v122, v119, vcc
	v_pk_mul_f32 v[112:113], v[112:113], v[122:123] op_sel_hi:[1,0]
	v_pk_mul_f32 v[114:115], v[114:115], v[122:123] op_sel_hi:[1,0]
	v_pk_mul_f32 v[104:105], v[104:105], v[122:123] op_sel_hi:[1,0]
	v_pk_mul_f32 v[106:107], v[106:107], v[122:123] op_sel_hi:[1,0]
; __device__ __forceinline__ unsigned pk2(float lo, float hi) { f32x2 v = {lo, hi}; bf16x2_t b = __builtin_convertvector(v, bf16x2_t); return __builtin_bit_cast(unsigned, b); }
; __device__ __forceinline__ float ex2(float x) { return __builtin_amdgcn_exp2f(x); }
; __device__ __forceinline__ float rcpf_(float x) { return __builtin_amdgcn_rcpf(x); }
; __device__ __forceinline__ float ssf(const ssq_t* p) { return (float)(*p) * (1.0f / 1048576.0f); }
;     __device__ __forceinline__ void operator()(const f32x4 (&acc)[2][2][4][2], const pg8::Unit& u, int wr, int wc, int fr, int fq) const {
; #pragma unroll
;         for (int ai = 0; ai < 2; ++ai)
; #pragma unroll
;             for (int m = 0; m < 4; ++m) {
;                 const int row = u.pm * 256 + ai * 128 + wr * 64 + m * 16 + fr;
;                 const float r = rsqrtf(ssf(SSin + row) * (1.0f / D) + EPS);
;                 const int col = u.pn * 128 + wc * 32 + fq * 8;
;                 float v[8];
; #pragma unroll
;                 for (int n = 0; n < 2; ++n) {
;                     const f32x4 g = acc[ai][0][m][n] * r, up = acc[ai][1][m][n] * r;
; #pragma unroll
;                     for (int i = 0; i < 4; ++i) v[4 * n + i] = g[i] * rcpf_(1.0f + ex2(-g[i] * LOG2E)) * up[i];
;                 }
;                 u32x4 w; w.x = pk2(v[0], v[1]); w.y = pk2(v[2], v[3]); w.z = pk2(v[4], v[5]); w.w = pk2(v[6], v[7]);
;                 *(u32x4*)(O + (size_t)row * FF + col) = w;
;             }
	v_pk_mul_f32 v[108:109], v[108:109], v[122:123] op_sel_hi:[1,0]
	v_pk_mul_f32 v[110:111], v[110:111], v[122:123] op_sel_hi:[1,0]
	v_pk_mul_f32 v[100:101], v[100:101], v[122:123] op_sel_hi:[1,0]
	v_pk_mul_f32 v[102:103], v[102:103], v[122:123] op_sel_hi:[1,0]
	v_mul_f32_e32 v119, 0xbfb8aa3b, v112
	v_mul_f32_e32 v122, 0xbfb8aa3b, v113
	v_mul_f32_e32 v123, 0xbfb8aa3b, v114
	v_mul_f32_e32 v124, 0xbfb8aa3b, v115
	v_mul_f32_e32 v125, 0xbfb8aa3b, v104
	v_mul_f32_e32 v126, 0xbfb8aa3b, v105
	v_mul_f32_e32 v127, 0xbfb8aa3b, v106
	v_mul_f32_e32 v128, 0xbfb8aa3b, v107
	v_exp_f32_e32 v119, v119
	v_exp_f32_e32 v122, v122
	v_exp_f32_e32 v123, v123
	v_exp_f32_e32 v124, v124
	v_exp_f32_e32 v125, v125
	v_exp_f32_e32 v126, v126
	v_exp_f32_e32 v127, v127
	v_exp_f32_e32 v128, v128
	v_add_f32_e32 v119, 1.0, v119
	v_add_f32_e32 v129, 1.0, v122
	v_add_f32_e32 v130, 1.0, v123
	v_add_f32_e32 v131, 1.0, v124
	v_add_f32_e32 v147, 1.0, v125
	v_add_f32_e32 v154, 1.0, v126
	v_add_f32_e32 v155, 1.0, v127
	v_add_f32_e32 v156, 1.0, v128
	v_rcp_f32_e32 v122, v119
	v_rcp_f32_e32 v123, v129
	v_rcp_f32_e32 v124, v130
	v_rcp_f32_e32 v125, v131
	v_rcp_f32_e32 v126, v147
	v_rcp_f32_e32 v127, v154
	v_rcp_f32_e32 v128, v155
	v_rcp_f32_e32 v129, v156
	v_pk_mul_f32 v[112:113], v[112:113], v[122:123]
	v_pk_mul_f32 v[114:115], v[114:115], v[124:125]
	v_pk_mul_f32 v[104:105], v[104:105], v[126:127]
	v_pk_mul_f32 v[106:107], v[106:107], v[128:129]
	v_pk_mul_f32 v[108:109], v[108:109], v[112:113]
	v_pk_mul_f32 v[110:111], v[110:111], v[114:115]
	v_pk_mul_f32 v[104:105], v[100:101], v[104:105]
	v_pk_mul_f32 v[106:107], v[102:103], v[106:107]
	v_cvt_pk_bf16_f32 v100, v108, v109
	v_cvt_pk_bf16_f32 v101, v110, v111
	v_cvt_pk_bf16_f32 v102, v104, v105
	v_cvt_pk_bf16_f32 v103, v106, v107
	global_store_dwordx4 v[116:117], v[100:103], off
	s_nop 0
	s_nop 0
	v_add_u32_e32 v102, s2, v151
	s_nop 0
	v_ffbh_u32_e32 v103, v179
	v_min_u32_e32 v103, 32, v103
	v_lshlrev_b64 v[100:101], v103, v[178:179]
	v_min_u32_e32 v100, 1, v100
	v_or_b32_e32 v100, v101, v100
	v_cvt_f32_u32_e32 v104, v100
	v_sub_u32_e32 v103, 32, v103
	v_mad_i64_i32 v[100:101], s[2:3], v118, s1, v[142:143]
	v_ldexp_f32 v103, v104, v103
	v_mul_f32_e32 v103, 0x35800000, v103
	v_fmamk_f32 v103, v103, 0x3a800000, v196
	v_mul_f32_e32 v104, 0x4b800000, v103
	v_cmp_gt_f32_e32 vcc, s23, v103
	v_lshl_add_u64 v[100:101], v[100:101], 0, v[144:145]
	s_nop 0
	v_cndmask_b32_e32 v103, v103, v104, vcc
	v_rsq_f32_e32 v106, v103
	v_ashrrev_i32_e32 v103, 31, v102
	v_lshl_add_u64 v[104:105], v[102:103], 3, s[44:45]
	v_mul_f32_e32 v103, 0x45800000, v106
	v_cndmask_b32_e32 v106, v106, v103, vcc
	v_pk_mul_f32 v[94:95], v[94:95], v[106:107] op_sel_hi:[1,0]
	v_pk_mul_f32 v[96:97], v[96:97], v[106:107] op_sel_hi:[1,0]
	v_pk_mul_f32 v[86:87], v[86:87], v[106:107] op_sel_hi:[1,0]
	v_pk_mul_f32 v[88:89], v[88:89], v[106:107] op_sel_hi:[1,0]
	v_pk_mul_f32 v[90:91], v[90:91], v[106:107] op_sel_hi:[1,0]
	v_pk_mul_f32 v[92:93], v[92:93], v[106:107] op_sel_hi:[1,0]
	v_pk_mul_f32 v[82:83], v[82:83], v[106:107] op_sel_hi:[1,0]
	v_pk_mul_f32 v[84:85], v[84:85], v[106:107] op_sel_hi:[1,0]
	v_mul_f32_e32 v103, 0xbfb8aa3b, v94
	v_mul_f32_e32 v106, 0xbfb8aa3b, v95
	v_mul_f32_e32 v107, 0xbfb8aa3b, v96
	v_mul_f32_e32 v108, 0xbfb8aa3b, v97
	v_mul_f32_e32 v109, 0xbfb8aa3b, v86
	v_mul_f32_e32 v110, 0xbfb8aa3b, v87
	v_mul_f32_e32 v111, 0xbfb8aa3b, v88
	v_mul_f32_e32 v112, 0xbfb8aa3b, v89
	v_exp_f32_e32 v103, v103
	v_exp_f32_e32 v106, v106
	v_exp_f32_e32 v107, v107
	v_exp_f32_e32 v108, v108
	v_exp_f32_e32 v109, v109
	v_exp_f32_e32 v110, v110
	v_exp_f32_e32 v111, v111
	v_exp_f32_e32 v112, v112
	v_add_f32_e32 v103, 1.0, v103
	v_add_f32_e32 v113, 1.0, v106
	v_add_f32_e32 v114, 1.0, v107
	v_add_f32_e32 v115, 1.0, v108
	v_add_f32_e32 v116, 1.0, v109
	v_add_f32_e32 v117, 1.0, v110
	v_add_f32_e32 v118, 1.0, v111
	v_add_f32_e32 v119, 1.0, v112
	v_rcp_f32_e32 v106, v103
	v_rcp_f32_e32 v107, v113
	v_rcp_f32_e32 v108, v114
	v_rcp_f32_e32 v109, v115
	v_rcp_f32_e32 v110, v116
	v_rcp_f32_e32 v111, v117
	v_rcp_f32_e32 v112, v118
	v_rcp_f32_e32 v113, v119
	v_pk_mul_f32 v[94:95], v[94:95], v[106:107]
	v_pk_mul_f32 v[96:97], v[96:97], v[108:109]
	v_pk_mul_f32 v[86:87], v[86:87], v[110:111]
	v_pk_mul_f32 v[88:89], v[88:89], v[112:113]
	v_pk_mul_f32 v[90:91], v[90:91], v[94:95]
	v_pk_mul_f32 v[92:93], v[92:93], v[96:97]
	v_pk_mul_f32 v[86:87], v[82:83], v[86:87]
	v_pk_mul_f32 v[88:89], v[84:85], v[88:89]
	v_cvt_pk_bf16_f32 v82, v90, v91
	v_cvt_pk_bf16_f32 v83, v92, v93
	v_cvt_pk_bf16_f32 v84, v86, v87
	v_cvt_pk_bf16_f32 v85, v88, v89
	global_store_dwordx4 v[100:101], v[82:85], off
	s_nop 0
	s_nop 0
	v_ffbh_u32_e32 v84, v181
	v_min_u32_e32 v85, 32, v84
	v_lshlrev_b64 v[82:83], v85, v[180:181]
	v_min_u32_e32 v82, 1, v82
	v_or_b32_e32 v82, v83, v82
	v_cvt_f32_u32_e32 v86, v82
	v_sub_u32_e32 v85, 32, v85
	v_add_u32_e32 v84, 0x80, v146
	v_mad_i64_i32 v[82:83], s[2:3], v102, s1, v[142:143]
	v_ldexp_f32 v85, v86, v85
	v_mul_f32_e32 v85, 0x35800000, v85
	v_fmamk_f32 v85, v85, 0x3a800000, v196
	v_mul_f32_e32 v86, 0x4b800000, v85
	v_cmp_gt_f32_e32 vcc, s23, v85
	v_lshl_add_u64 v[82:83], v[82:83], 0, v[144:145]
	s_nop 0
	v_cndmask_b32_e32 v85, v85, v86, vcc
	v_rsq_f32_e32 v88, v85
	v_ashrrev_i32_e32 v85, 31, v84
	v_lshl_add_u64 v[86:87], v[84:85], 3, s[44:45]
	v_mul_f32_e32 v85, 0x45800000, v88
	v_cndmask_b32_e32 v88, v88, v85, vcc
	v_pk_mul_f32 v[78:79], v[78:79], v[88:89] op_sel_hi:[1,0]
	v_pk_mul_f32 v[80:81], v[80:81], v[88:89] op_sel_hi:[1,0]
	v_pk_mul_f32 v[70:71], v[70:71], v[88:89] op_sel_hi:[1,0]
	v_pk_mul_f32 v[72:73], v[72:73], v[88:89] op_sel_hi:[1,0]
	v_pk_mul_f32 v[74:75], v[74:75], v[88:89] op_sel_hi:[1,0]
; __device__ __forceinline__ unsigned pk2(float lo, float hi) { f32x2 v = {lo, hi}; bf16x2_t b = __builtin_convertvector(v, bf16x2_t); return __builtin_bit_cast(unsigned, b); }
; __device__ __forceinline__ float ex2(float x) { return __builtin_amdgcn_exp2f(x); }
; __device__ __forceinline__ float rcpf_(float x) { return __builtin_amdgcn_rcpf(x); }
; __device__ __forceinline__ float ssf(const ssq_t* p) { return (float)(*p) * (1.0f / 1048576.0f); }
;     __device__ __forceinline__ void operator()(const f32x4 (&acc)[2][2][4][2], const pg8::Unit& u, int wr, int wc, int fr, int fq) const {
; #pragma unroll
;         for (int ai = 0; ai < 2; ++ai)
; #pragma unroll
;             for (int m = 0; m < 4; ++m) {
;                 const int row = u.pm * 256 + ai * 128 + wr * 64 + m * 16 + fr;
;                 const float r = rsqrtf(ssf(SSin + row) * (1.0f / D) + EPS);
;                 const int col = u.pn * 128 + wc * 32 + fq * 8;
;                 float v[8];
; #pragma unroll
;                 for (int n = 0; n < 2; ++n) {
;                     const f32x4 g = acc[ai][0][m][n] * r, up = acc[ai][1][m][n] * r;
; #pragma unroll
;                     for (int i = 0; i < 4; ++i) v[4 * n + i] = g[i] * rcpf_(1.0f + ex2(-g[i] * LOG2E)) * up[i];
;                 }
;                 u32x4 w; w.x = pk2(v[0], v[1]); w.y = pk2(v[2], v[3]); w.z = pk2(v[4], v[5]); w.w = pk2(v[6], v[7]);
;                 *(u32x4*)(O + (size_t)row * FF + col) = w;
;             }
	v_pk_mul_f32 v[76:77], v[76:77], v[88:89] op_sel_hi:[1,0]
	v_pk_mul_f32 v[66:67], v[66:67], v[88:89] op_sel_hi:[1,0]
	v_pk_mul_f32 v[68:69], v[68:69], v[88:89] op_sel_hi:[1,0]
	v_mul_f32_e32 v85, 0xbfb8aa3b, v78
	v_mul_f32_e32 v88, 0xbfb8aa3b, v79
	v_mul_f32_e32 v89, 0xbfb8aa3b, v80
	v_mul_f32_e32 v90, 0xbfb8aa3b, v81
	v_mul_f32_e32 v91, 0xbfb8aa3b, v70
	v_mul_f32_e32 v92, 0xbfb8aa3b, v71
	v_mul_f32_e32 v93, 0xbfb8aa3b, v72
	v_mul_f32_e32 v94, 0xbfb8aa3b, v73
	v_exp_f32_e32 v85, v85
	v_exp_f32_e32 v88, v88
	v_exp_f32_e32 v89, v89
	v_exp_f32_e32 v90, v90
	v_exp_f32_e32 v91, v91
	v_exp_f32_e32 v92, v92
	v_exp_f32_e32 v93, v93
	v_exp_f32_e32 v94, v94
	v_add_f32_e32 v85, 1.0, v85
	v_add_f32_e32 v95, 1.0, v88
	v_add_f32_e32 v96, 1.0, v89
	v_add_f32_e32 v97, 1.0, v90
	v_add_f32_e32 v100, 1.0, v91
	v_add_f32_e32 v101, 1.0, v92
	v_add_f32_e32 v102, 1.0, v93
	v_add_f32_e32 v103, 1.0, v94
	v_rcp_f32_e32 v88, v85
	v_rcp_f32_e32 v89, v95
	v_rcp_f32_e32 v90, v96
	v_rcp_f32_e32 v91, v97
	v_rcp_f32_e32 v92, v100
	v_rcp_f32_e32 v93, v101
	v_rcp_f32_e32 v94, v102
	v_rcp_f32_e32 v95, v103
	v_pk_mul_f32 v[78:79], v[78:79], v[88:89]
	v_pk_mul_f32 v[80:81], v[80:81], v[90:91]
	v_pk_mul_f32 v[70:71], v[70:71], v[92:93]
	v_pk_mul_f32 v[72:73], v[72:73], v[94:95]
	v_pk_mul_f32 v[74:75], v[74:75], v[78:79]
	v_pk_mul_f32 v[76:77], v[76:77], v[80:81]
	v_pk_mul_f32 v[70:71], v[66:67], v[70:71]
	v_pk_mul_f32 v[72:73], v[68:69], v[72:73]
	v_cvt_pk_bf16_f32 v66, v74, v75
	v_cvt_pk_bf16_f32 v67, v76, v77
	v_cvt_pk_bf16_f32 v68, v70, v71
	v_cvt_pk_bf16_f32 v69, v72, v73
	global_store_dwordx4 v[82:83], v[66:69], off
	s_nop 0
	s_nop 0
	v_add_u32_e32 v68, 0x90, v146
	s_nop 0
	v_ffbh_u32_e32 v69, v183
	v_min_u32_e32 v69, 32, v69
	v_lshlrev_b64 v[66:67], v69, v[182:183]
	v_min_u32_e32 v66, 1, v66
	v_or_b32_e32 v66, v67, v66
	v_cvt_f32_u32_e32 v70, v66
	v_sub_u32_e32 v69, 32, v69
	v_mad_i64_i32 v[66:67], s[2:3], v84, s1, v[142:143]
	v_ldexp_f32 v69, v70, v69
	v_mul_f32_e32 v69, 0x35800000, v69
	v_fmamk_f32 v69, v69, 0x3a800000, v196
	v_mul_f32_e32 v70, 0x4b800000, v69
	v_cmp_gt_f32_e32 vcc, s23, v69
	v_lshl_add_u64 v[66:67], v[66:67], 0, v[144:145]
	s_nop 0
	v_cndmask_b32_e32 v69, v69, v70, vcc
	v_rsq_f32_e32 v72, v69
	v_ashrrev_i32_e32 v69, 31, v68
	v_lshl_add_u64 v[70:71], v[68:69], 3, s[44:45]
	v_mul_f32_e32 v69, 0x45800000, v72
	v_cndmask_b32_e32 v72, v72, v69, vcc
	v_pk_mul_f32 v[62:63], v[62:63], v[72:73] op_sel_hi:[1,0]
	v_pk_mul_f32 v[64:65], v[64:65], v[72:73] op_sel_hi:[1,0]
	v_pk_mul_f32 v[54:55], v[54:55], v[72:73] op_sel_hi:[1,0]
	v_pk_mul_f32 v[56:57], v[56:57], v[72:73] op_sel_hi:[1,0]
	v_pk_mul_f32 v[58:59], v[58:59], v[72:73] op_sel_hi:[1,0]
	v_pk_mul_f32 v[60:61], v[60:61], v[72:73] op_sel_hi:[1,0]
	v_pk_mul_f32 v[50:51], v[50:51], v[72:73] op_sel_hi:[1,0]
	v_pk_mul_f32 v[52:53], v[52:53], v[72:73] op_sel_hi:[1,0]
	v_mul_f32_e32 v69, 0xbfb8aa3b, v62
	v_mul_f32_e32 v72, 0xbfb8aa3b, v63
	v_mul_f32_e32 v73, 0xbfb8aa3b, v64
	v_mul_f32_e32 v74, 0xbfb8aa3b, v65
	v_mul_f32_e32 v75, 0xbfb8aa3b, v54
	v_mul_f32_e32 v76, 0xbfb8aa3b, v55
	v_mul_f32_e32 v77, 0xbfb8aa3b, v56
	v_mul_f32_e32 v78, 0xbfb8aa3b, v57
	v_exp_f32_e32 v69, v69
	v_exp_f32_e32 v72, v72
	v_exp_f32_e32 v73, v73
	v_exp_f32_e32 v74, v74
	v_exp_f32_e32 v75, v75
	v_exp_f32_e32 v76, v76
	v_exp_f32_e32 v77, v77
	v_exp_f32_e32 v78, v78
	v_add_f32_e32 v69, 1.0, v69
	v_add_f32_e32 v79, 1.0, v72
	v_add_f32_e32 v80, 1.0, v73
	v_add_f32_e32 v81, 1.0, v74
	v_add_f32_e32 v82, 1.0, v75
	v_add_f32_e32 v83, 1.0, v76
	v_add_f32_e32 v84, 1.0, v77
	v_add_f32_e32 v85, 1.0, v78
	v_rcp_f32_e32 v72, v69
	v_rcp_f32_e32 v73, v79
	v_rcp_f32_e32 v74, v80
	v_rcp_f32_e32 v75, v81
	v_rcp_f32_e32 v76, v82
	v_rcp_f32_e32 v77, v83
	v_rcp_f32_e32 v78, v84
	v_rcp_f32_e32 v79, v85
	v_pk_mul_f32 v[62:63], v[62:63], v[72:73]
	v_pk_mul_f32 v[64:65], v[64:65], v[74:75]
	v_pk_mul_f32 v[54:55], v[54:55], v[76:77]
	v_pk_mul_f32 v[56:57], v[56:57], v[78:79]
	v_pk_mul_f32 v[58:59], v[58:59], v[62:63]
	v_pk_mul_f32 v[60:61], v[60:61], v[64:65]
	v_pk_mul_f32 v[54:55], v[50:51], v[54:55]
	v_pk_mul_f32 v[56:57], v[52:53], v[56:57]
	v_cvt_pk_bf16_f32 v50, v58, v59
	v_cvt_pk_bf16_f32 v51, v60, v61
	v_cvt_pk_bf16_f32 v52, v54, v55
	v_cvt_pk_bf16_f32 v53, v56, v57
	global_store_dwordx4 v[66:67], v[50:53], off
	s_nop 0
	s_nop 0
	v_add_u32_e32 v52, 0xa0, v146
	s_nop 0
	v_ffbh_u32_e32 v53, v185
	v_min_u32_e32 v53, 32, v53
	v_lshlrev_b64 v[50:51], v53, v[184:185]
	v_min_u32_e32 v50, 1, v50
	v_or_b32_e32 v50, v51, v50
	v_cvt_f32_u32_e32 v54, v50
	v_sub_u32_e32 v53, 32, v53
	v_mad_i64_i32 v[50:51], s[2:3], v68, s1, v[142:143]
	v_ldexp_f32 v53, v54, v53
	v_mul_f32_e32 v53, 0x35800000, v53
	v_fmamk_f32 v53, v53, 0x3a800000, v196
	v_mul_f32_e32 v54, 0x4b800000, v53
	v_cmp_gt_f32_e32 vcc, s23, v53
	v_lshl_add_u64 v[50:51], v[50:51], 0, v[144:145]
	s_nop 0
	v_cndmask_b32_e32 v53, v53, v54, vcc
	v_rsq_f32_e32 v56, v53
	v_ashrrev_i32_e32 v53, 31, v52
	v_lshl_add_u64 v[54:55], v[52:53], 3, s[44:45]
	v_mul_f32_e32 v53, 0x45800000, v56
	v_cndmask_b32_e32 v56, v56, v53, vcc
	v_pk_mul_f32 v[46:47], v[46:47], v[56:57] op_sel_hi:[1,0]
	v_pk_mul_f32 v[48:49], v[48:49], v[56:57] op_sel_hi:[1,0]
	v_pk_mul_f32 v[38:39], v[38:39], v[56:57] op_sel_hi:[1,0]
	v_pk_mul_f32 v[40:41], v[40:41], v[56:57] op_sel_hi:[1,0]
	v_pk_mul_f32 v[42:43], v[42:43], v[56:57] op_sel_hi:[1,0]
	v_pk_mul_f32 v[44:45], v[44:45], v[56:57] op_sel_hi:[1,0]
	v_pk_mul_f32 v[34:35], v[34:35], v[56:57] op_sel_hi:[1,0]
	v_pk_mul_f32 v[36:37], v[36:37], v[56:57] op_sel_hi:[1,0]
	v_mul_f32_e32 v53, 0xbfb8aa3b, v46
	v_mul_f32_e32 v56, 0xbfb8aa3b, v47
	v_mul_f32_e32 v57, 0xbfb8aa3b, v48
	v_mul_f32_e32 v58, 0xbfb8aa3b, v49
; __device__ __forceinline__ unsigned pk2(float lo, float hi) { f32x2 v = {lo, hi}; bf16x2_t b = __builtin_convertvector(v, bf16x2_t); return __builtin_bit_cast(unsigned, b); }
; __device__ __forceinline__ float ex2(float x) { return __builtin_amdgcn_exp2f(x); }
; __device__ __forceinline__ float rcpf_(float x) { return __builtin_amdgcn_rcpf(x); }
; __device__ __forceinline__ float ssf(const ssq_t* p) { return (float)(*p) * (1.0f / 1048576.0f); }
;     __device__ __forceinline__ void operator()(const f32x4 (&acc)[2][2][4][2], const pg8::Unit& u, int wr, int wc, int fr, int fq) const {
; #pragma unroll
;         for (int ai = 0; ai < 2; ++ai)
; #pragma unroll
;             for (int m = 0; m < 4; ++m) {
;                 const int row = u.pm * 256 + ai * 128 + wr * 64 + m * 16 + fr;
;                 const float r = rsqrtf(ssf(SSin + row) * (1.0f / D) + EPS);
;                 const int col = u.pn * 128 + wc * 32 + fq * 8;
;                 float v[8];
; #pragma unroll
;                 for (int n = 0; n < 2; ++n) {
;                     const f32x4 g = acc[ai][0][m][n] * r, up = acc[ai][1][m][n] * r;
; #pragma unroll
;                     for (int i = 0; i < 4; ++i) v[4 * n + i] = g[i] * rcpf_(1.0f + ex2(-g[i] * LOG2E)) * up[i];
;                 }
;                 u32x4 w; w.x = pk2(v[0], v[1]); w.y = pk2(v[2], v[3]); w.z = pk2(v[4], v[5]); w.w = pk2(v[6], v[7]);
;                 *(u32x4*)(O + (size_t)row * FF + col) = w;
;             }
	v_mul_f32_e32 v59, 0xbfb8aa3b, v38
	v_mul_f32_e32 v60, 0xbfb8aa3b, v39
	v_mul_f32_e32 v61, 0xbfb8aa3b, v40
	v_mul_f32_e32 v62, 0xbfb8aa3b, v41
	v_exp_f32_e32 v53, v53
	v_exp_f32_e32 v56, v56
	v_exp_f32_e32 v57, v57
	v_exp_f32_e32 v58, v58
	v_exp_f32_e32 v59, v59
	v_exp_f32_e32 v60, v60
	v_exp_f32_e32 v61, v61
	v_exp_f32_e32 v62, v62
	v_add_f32_e32 v53, 1.0, v53
	v_add_f32_e32 v63, 1.0, v56
	v_add_f32_e32 v64, 1.0, v57
	v_add_f32_e32 v65, 1.0, v58
	v_add_f32_e32 v66, 1.0, v59
	v_add_f32_e32 v67, 1.0, v60
	v_add_f32_e32 v68, 1.0, v61
	v_add_f32_e32 v69, 1.0, v62
	v_rcp_f32_e32 v56, v53
	v_rcp_f32_e32 v57, v63
	v_rcp_f32_e32 v58, v64
	v_rcp_f32_e32 v59, v65
	v_rcp_f32_e32 v60, v66
	v_rcp_f32_e32 v61, v67
	v_rcp_f32_e32 v62, v68
	v_rcp_f32_e32 v63, v69
	v_pk_mul_f32 v[46:47], v[46:47], v[56:57]
	v_pk_mul_f32 v[48:49], v[48:49], v[58:59]
	v_pk_mul_f32 v[38:39], v[38:39], v[60:61]
	v_pk_mul_f32 v[40:41], v[40:41], v[62:63]
	v_pk_mul_f32 v[42:43], v[42:43], v[46:47]
	v_pk_mul_f32 v[44:45], v[44:45], v[48:49]
	v_pk_mul_f32 v[38:39], v[34:35], v[38:39]
	v_pk_mul_f32 v[40:41], v[36:37], v[40:41]
	v_cvt_pk_bf16_f32 v34, v42, v43
	v_cvt_pk_bf16_f32 v35, v44, v45
	v_cvt_pk_bf16_f32 v36, v38, v39
	v_cvt_pk_bf16_f32 v37, v40, v41
	global_store_dwordx4 v[50:51], v[34:37], off
	s_nop 0
	s_nop 0
	v_add_u32_e32 v36, 0xb0, v146
	s_nop 0
	v_ffbh_u32_e32 v37, v187
	v_min_u32_e32 v37, 32, v37
	v_lshlrev_b64 v[34:35], v37, v[186:187]
	v_min_u32_e32 v34, 1, v34
	v_or_b32_e32 v34, v35, v34
	v_cvt_f32_u32_e32 v38, v34
	v_sub_u32_e32 v37, 32, v37
	v_mad_i64_i32 v[34:35], s[2:3], v52, s1, v[142:143]
	v_ldexp_f32 v37, v38, v37
	v_mul_f32_e32 v37, 0x35800000, v37
	v_fmamk_f32 v37, v37, 0x3a800000, v196
	v_mul_f32_e32 v38, 0x4b800000, v37
	v_cmp_gt_f32_e32 vcc, s23, v37
	v_lshl_add_u64 v[34:35], v[34:35], 0, v[144:145]
	s_nop 0
	v_cndmask_b32_e32 v37, v37, v38, vcc
	v_rsq_f32_e32 v40, v37
	v_ashrrev_i32_e32 v37, 31, v36
	v_lshl_add_u64 v[38:39], v[36:37], 3, s[44:45]
	v_mul_f32_e32 v37, 0x45800000, v40
	v_cndmask_b32_e32 v40, v40, v37, vcc
	v_pk_mul_f32 v[30:31], v[30:31], v[40:41] op_sel_hi:[1,0]
	v_pk_mul_f32 v[32:33], v[32:33], v[40:41] op_sel_hi:[1,0]
	v_pk_mul_f32 v[22:23], v[22:23], v[40:41] op_sel_hi:[1,0]
	v_pk_mul_f32 v[24:25], v[24:25], v[40:41] op_sel_hi:[1,0]
	v_pk_mul_f32 v[26:27], v[26:27], v[40:41] op_sel_hi:[1,0]
	v_pk_mul_f32 v[28:29], v[28:29], v[40:41] op_sel_hi:[1,0]
	v_pk_mul_f32 v[18:19], v[18:19], v[40:41] op_sel_hi:[1,0]
	v_pk_mul_f32 v[20:21], v[20:21], v[40:41] op_sel_hi:[1,0]
	v_mul_f32_e32 v37, 0xbfb8aa3b, v30
	v_mul_f32_e32 v40, 0xbfb8aa3b, v31
	v_mul_f32_e32 v41, 0xbfb8aa3b, v32
	v_mul_f32_e32 v42, 0xbfb8aa3b, v33
	v_mul_f32_e32 v43, 0xbfb8aa3b, v22
	v_mul_f32_e32 v44, 0xbfb8aa3b, v23
	v_mul_f32_e32 v45, 0xbfb8aa3b, v24
	v_mul_f32_e32 v46, 0xbfb8aa3b, v25
	v_exp_f32_e32 v37, v37
	v_exp_f32_e32 v40, v40
	v_exp_f32_e32 v41, v41
	v_exp_f32_e32 v42, v42
	v_exp_f32_e32 v43, v43
	v_exp_f32_e32 v44, v44
	v_exp_f32_e32 v45, v45
	v_exp_f32_e32 v46, v46
	v_add_f32_e32 v37, 1.0, v37
	v_add_f32_e32 v47, 1.0, v40
	v_add_f32_e32 v48, 1.0, v41
	v_add_f32_e32 v49, 1.0, v42
	v_add_f32_e32 v50, 1.0, v43
	v_add_f32_e32 v51, 1.0, v44
	v_add_f32_e32 v52, 1.0, v45
	v_add_f32_e32 v53, 1.0, v46
	v_rcp_f32_e32 v40, v37
	v_rcp_f32_e32 v41, v47
	v_rcp_f32_e32 v42, v48
	v_rcp_f32_e32 v43, v49
	v_rcp_f32_e32 v44, v50
	v_rcp_f32_e32 v45, v51
	v_rcp_f32_e32 v46, v52
	v_rcp_f32_e32 v47, v53
	v_pk_mul_f32 v[30:31], v[30:31], v[40:41]
	v_pk_mul_f32 v[32:33], v[32:33], v[42:43]
	v_pk_mul_f32 v[22:23], v[22:23], v[44:45]
	v_pk_mul_f32 v[24:25], v[24:25], v[46:47]
	v_pk_mul_f32 v[26:27], v[26:27], v[30:31]
	v_pk_mul_f32 v[28:29], v[28:29], v[32:33]
	v_pk_mul_f32 v[22:23], v[18:19], v[22:23]
	v_pk_mul_f32 v[24:25], v[20:21], v[24:25]
	v_cvt_pk_bf16_f32 v18, v26, v27
	v_cvt_pk_bf16_f32 v19, v28, v29
	v_cvt_pk_bf16_f32 v20, v22, v23
	v_cvt_pk_bf16_f32 v21, v24, v25
	global_store_dwordx4 v[34:35], v[18:21], off
	s_nop 0
	s_and_b64 vcc, exec, s[42:43]
	s_nop 0
	v_ffbh_u32_e32 v20, v189
	v_min_u32_e32 v20, 32, v20
	v_lshlrev_b64 v[18:19], v20, v[188:189]
	v_min_u32_e32 v18, 1, v18
	v_or_b32_e32 v18, v19, v18
	v_cvt_f32_u32_e32 v18, v18
	v_sub_u32_e32 v19, 32, v20
	v_ldexp_f32 v18, v18, v19
	v_mul_f32_e32 v18, 0x35800000, v18
	v_fmamk_f32 v18, v18, 0x3a800000, v196
	v_mul_f32_e32 v19, 0x4b800000, v18
	v_cmp_gt_f32_e64 s[2:3], s23, v18
	s_nop 1
	v_cndmask_b32_e64 v18, v18, v19, s[2:3]
	v_rsq_f32_e32 v20, v18
	v_mad_i64_i32 v[18:19], s[16:17], v36, s1, v[142:143]
	v_lshl_add_u64 v[18:19], v[18:19], 0, v[144:145]
	v_mul_f32_e32 v21, 0x45800000, v20
	v_cndmask_b32_e64 v20, v20, v21, s[2:3]
	v_pk_mul_f32 v[14:15], v[14:15], v[20:21] op_sel_hi:[1,0]
	v_pk_mul_f32 v[16:17], v[16:17], v[20:21] op_sel_hi:[1,0]
	v_pk_mul_f32 v[6:7], v[6:7], v[20:21] op_sel_hi:[1,0]
	v_pk_mul_f32 v[8:9], v[8:9], v[20:21] op_sel_hi:[1,0]
	v_pk_mul_f32 v[10:11], v[10:11], v[20:21] op_sel_hi:[1,0]
	v_pk_mul_f32 v[12:13], v[12:13], v[20:21] op_sel_hi:[1,0]
	v_pk_mul_f32 v[2:3], v[2:3], v[20:21] op_sel_hi:[1,0]
	v_pk_mul_f32 v[4:5], v[4:5], v[20:21] op_sel_hi:[1,0]
	v_mul_f32_e32 v20, 0xbfb8aa3b, v14
	v_mul_f32_e32 v21, 0xbfb8aa3b, v15
	v_mul_f32_e32 v22, 0xbfb8aa3b, v16
	v_mul_f32_e32 v23, 0xbfb8aa3b, v17
	v_mul_f32_e32 v24, 0xbfb8aa3b, v6
	v_mul_f32_e32 v25, 0xbfb8aa3b, v7
	v_mul_f32_e32 v26, 0xbfb8aa3b, v8
	v_mul_f32_e32 v27, 0xbfb8aa3b, v9
	v_exp_f32_e32 v20, v20
	v_exp_f32_e32 v21, v21
	v_exp_f32_e32 v22, v22
	v_exp_f32_e32 v23, v23
	v_exp_f32_e32 v24, v24
	v_exp_f32_e32 v25, v25
	v_exp_f32_e32 v26, v26
	v_exp_f32_e32 v27, v27
	v_add_f32_e32 v20, 1.0, v20
	v_add_f32_e32 v21, 1.0, v21
	v_add_f32_e32 v22, 1.0, v22
	v_add_f32_e32 v23, 1.0, v23
	v_add_f32_e32 v24, 1.0, v24
	v_add_f32_e32 v25, 1.0, v25
	v_add_f32_e32 v26, 1.0, v26
	v_add_f32_e32 v27, 1.0, v27
	v_rcp_f32_e32 v20, v20
	v_rcp_f32_e32 v21, v21
	v_rcp_f32_e32 v22, v22
	v_rcp_f32_e32 v23, v23
	v_rcp_f32_e32 v24, v24
	v_rcp_f32_e32 v25, v25
	v_rcp_f32_e32 v26, v26
	v_rcp_f32_e32 v27, v27
	v_pk_mul_f32 v[14:15], v[14:15], v[20:21]
	v_pk_mul_f32 v[16:17], v[16:17], v[22:23]
	v_pk_mul_f32 v[6:7], v[6:7], v[24:25]
	v_pk_mul_f32 v[8:9], v[8:9], v[26:27]
	v_pk_mul_f32 v[10:11], v[10:11], v[14:15]
	v_pk_mul_f32 v[12:13], v[12:13], v[16:17]
	v_pk_mul_f32 v[6:7], v[2:3], v[6:7]
	v_pk_mul_f32 v[8:9], v[4:5], v[8:9]
	v_cvt_pk_bf16_f32 v2, v10, v11
	v_cvt_pk_bf16_f32 v3, v12, v13
	v_cvt_pk_bf16_f32 v4, v6, v7
	v_cvt_pk_bf16_f32 v5, v8, v9
	s_mov_b64 s[2:3], -1
	global_store_dwordx4 v[18:19], v[2:5], off
	s_cbranch_vccnz .LBB0_1474
	s_andn2_b64 vcc, exec, s[14:15]
	s_cbranch_vccnz .LBB0_1473
	s_barrier
	s_branch .LBB0_1473
